# 64-byte alignment of the seven hot loop heads (5 GEMM K-loops, N2 step loop, P3 expert loop); on top of v37
# speedup vs baseline: 1.0036x; 1.0036x over previous
; #define TIDX512 launder_i((int)threadIdx.x)
; __device__ __forceinline__ void glds16(const bf16_t* g, char* l) { __builtin_amdgcn_global_load_lds((const unsigned*)g, (unsigned*)l, 16, 0, 0); }
; __device__ __forceinline__ void gemm_issue(const GemmSrc& g, int kt, int s, char* lds) {
;     const int tid = TIDX512, lane = tid & 63, wave = tid >> 6;
;     char* xdst = lds + s * 65536 + wave * 4096 + lane * 16;
;     char* wdst = xdst + 32768;
; #pragma unroll
;     for (int i = 0; i < 4; i++) {
;         const int d = (i & 1) ? g.dsw : 0;
;         glds16(g.xsrc + (size_t)i * 8 * g.ldx + kt * 64 + d, xdst + i * 1024);
;         glds16(g.wsrc + (size_t)i * 8 * g.ldw + kt * 64 + d, wdst + i * 1024);
;     }
; }
; __device__ __forceinline__ void gemm_prologue(const GemmSrc& g, char* lds) { gemm_issue(g, 0, 0, lds); }
; __device__ __forceinline__ void zero_acc(f32x4 (&acc)[8][4]) {
; #pragma unroll
;     for (int a = 0; a < 8; a++)
; #pragma unroll
;         for (int b = 0; b < 4; b++) acc[a][b] = (f32x4){0.f, 0.f, 0.f, 0.f};
; }
.LBB0_298:
	s_andn2_b64 vcc, exec, s[8:9]
	s_mov_b64 s[8:9], -1
	s_cbranch_vccnz .LBB0_290
	v_mov_b32_e32 v0, v158
	s_lshl_b32 s82, s74, 8
	v_ashrrev_i32_e32 v1, 1, v0
	v_and_b32_e32 v12, 0xffffffe0, v1
	v_bfe_u32 v1, v0, 4, 2
	v_and_b32_e32 v3, 7, v0
	v_bitop3_b32 v4, v1, v0, 7 bitop3:0x78
	v_bitop3_b32 v5, v1, v3, 4 bitop3:0x36
	v_lshlrev_b32_e32 v128, 4, v4
	v_sub_u32_e32 v4, v5, v4
	v_mov_b32_e32 v5, v158
	v_bfe_u32 v13, v0, 3, 3
	v_or_b32_e32 v2, v12, v13
	v_lshlrev_b32_e32 v6, 6, v5
	v_lshlrev_b32_e32 v5, 4, v5
	s_lshl_b32 s44, s75, 8
	v_add_u32_e32 v0, s82, v2
	v_and_b32_e32 v5, 0x3f0, v5
	v_ashrrev_i32_e32 v1, 31, v0
	v_add_u32_e32 v2, s44, v2
	v_and_or_b32 v14, v6, s51, v5
	v_lshlrev_b64 v[0:1], 11, v[0:1]
	v_ashrrev_i32_e32 v3, 31, v2
	v_lshlrev_b32_e32 v4, 3, v4
	v_add_u32_e32 v5, 0x8000, v14
	v_readfirstlane_b32 s0, v14
	v_lshl_add_u64 v[0:1], s[14:15], 0, v[0:1]
	v_lshlrev_b64 v[2:3], 11, v[2:3]
	s_mov_b32 m0, s0
	v_readfirstlane_b32 s0, v5
	v_ashrrev_i32_e32 v5, 31, v4
	v_lshl_add_u64 v[0:1], v[0:1], 0, v[128:129]
	v_lshl_add_u64 v[2:3], s[16:17], 0, v[2:3]
	v_lshlrev_b64 v[4:5], 1, v[4:5]
	v_or_b32_e32 v10, 0x400, v14
	v_lshl_add_u64 v[2:3], v[2:3], 0, v[128:129]
	global_load_lds_dwordx4 v[0:1], off
	s_mov_b32 m0, s0
	v_lshl_add_u64 v[6:7], v[0:1], 0, v[4:5]
	v_readfirstlane_b32 s0, v10
	global_load_lds_dwordx4 v[2:3], off
	v_lshl_add_u64 v[8:9], v[6:7], 0, s[20:21]
	s_mov_b32 m0, s0
	v_add_u32_e32 v15, 0x8400, v14
	global_load_lds_dwordx4 v[8:9], off
	v_lshl_add_u64 v[8:9], v[2:3], 0, v[4:5]
	v_readfirstlane_b32 s0, v15
	v_lshl_add_u64 v[10:11], v[8:9], 0, s[20:21]
	s_mov_b32 m0, s0
	v_lshl_add_u64 v[0:1], v[0:1], 0, s[22:23]
	global_load_lds_dwordx4 v[10:11], off
	v_or_b32_e32 v10, 0x800, v14
	s_mov_b64 s[8:9], 0
	v_readfirstlane_b32 s0, v10
	s_mov_b32 m0, s0
	s_nop 0
	global_load_lds_dwordx4 v[0:1], off
	v_lshl_add_u64 v[0:1], v[2:3], 0, s[22:23]
	v_add_u32_e32 v2, 0x8800, v14
	s_nop 0
	v_readfirstlane_b32 s0, v2
	v_or_b32_e32 v2, 0xc00, v14
	s_mov_b32 m0, s0
	v_readfirstlane_b32 s0, v2
	v_add_u32_e32 v2, 0x8c00, v14
	global_load_lds_dwordx4 v[0:1], off
	v_lshl_add_u64 v[0:1], v[6:7], 0, s[24:25]
	s_mov_b32 m0, s0
	v_readfirstlane_b32 s0, v2
	global_load_lds_dwordx4 v[0:1], off
	v_lshl_add_u64 v[0:1], v[8:9], 0, s[24:25]
	s_mov_b32 m0, s0
	s_mov_b32 s0, 0x10000
	global_load_lds_dwordx4 v[0:1], off
	v_mov_b32_e32 v0, v158
	s_nop 0
	v_and_b32_e32 v1, 15, v0
	v_lshrrev_b32_e32 v2, 4, v0
	v_bfe_u32 v6, v0, 1, 3
	v_bfe_u32 v3, v0, 4, 2
	v_lshlrev_b32_e32 v1, 7, v1
	v_bitop3_b32 v2, v2, v6, 3 bitop3:0x6c
	v_lshl_or_b32 v142, v2, 4, v1
	v_bitop3_b32 v2, v3, v6, 4 bitop3:0x36
	v_lshl_or_b32 v133, v2, 4, v1
	v_lshlrev_b32_e32 v1, 7, v0
	v_lshlrev_b32_e32 v0, 6, v0
	v_and_b32_e32 v143, 0xffffc000, v0
	v_or_b32_e32 v0, s82, v13
	v_add_u32_e32 v0, v0, v12
	v_or_b32_e32 v2, s44, v13
	v_and_b32_e32 v144, 0x6000, v1
	v_ashrrev_i32_e32 v1, 31, v0
	v_add_u32_e32 v2, v2, v12
	v_lshlrev_b64 v[0:1], 11, v[0:1]
	v_ashrrev_i32_e32 v3, 31, v2
	v_or_b32_e32 v0, v0, v128
	v_lshlrev_b64 v[2:3], 11, v[2:3]
	v_lshl_add_u64 v[134:135], s[10:11], 0, v[0:1]
	v_or_b32_e32 v2, v2, v128
	v_lshl_add_u64 v[0:1], v[0:1], 0, v[4:5]
	v_lshl_add_u64 v[138:139], s[10:11], 0, v[0:1]
	v_lshl_add_u64 v[0:1], v[2:3], 0, v[4:5]
	v_lshl_add_u64 v[140:141], s[10:11], 0, v[0:1]
	v_mov_b32_e32 v0, 0
	v_lshl_add_u64 v[136:137], s[10:11], 0, v[2:3]
	v_mov_b32_e32 v1, v0
	v_mov_b32_e32 v2, v0
	v_mov_b32_e32 v3, v0
	v_mov_b32_e32 v4, v0
	v_mov_b32_e32 v5, v0
	v_mov_b32_e32 v6, v0
	v_mov_b32_e32 v7, v0
	v_mov_b32_e32 v8, v0
	v_mov_b32_e32 v9, v0
	v_mov_b32_e32 v10, v0
	v_mov_b32_e32 v11, v0
	v_mov_b32_e32 v12, v0
	v_mov_b32_e32 v13, v0
	v_mov_b32_e32 v14, v0
	v_mov_b32_e32 v15, v0
	v_mov_b32_e32 v16, v0
	v_mov_b32_e32 v17, v0
	v_mov_b32_e32 v18, v0
	v_mov_b32_e32 v19, v0
	v_mov_b32_e32 v20, v0
	v_mov_b32_e32 v21, v0
	v_mov_b32_e32 v22, v0
	v_mov_b32_e32 v23, v0
	v_mov_b32_e32 v24, v0
	v_mov_b32_e32 v25, v0
	v_mov_b32_e32 v26, v0
	v_mov_b32_e32 v27, v0
	v_mov_b32_e32 v28, v0
	v_mov_b32_e32 v29, v0
	v_mov_b32_e32 v30, v0
	v_mov_b32_e32 v31, v0
	v_mov_b32_e32 v32, v0
	v_mov_b32_e32 v33, v0
	v_mov_b32_e32 v34, v0
	v_mov_b32_e32 v35, v0
	v_mov_b32_e32 v36, v0
	v_mov_b32_e32 v37, v0
	v_mov_b32_e32 v38, v0
	v_mov_b32_e32 v39, v0
	v_mov_b32_e32 v40, v0
	v_mov_b32_e32 v41, v0
	v_mov_b32_e32 v42, v0
	v_mov_b32_e32 v43, v0
	v_mov_b32_e32 v44, v0
	v_mov_b32_e32 v45, v0
	v_mov_b32_e32 v46, v0
	v_mov_b32_e32 v47, v0
	v_mov_b32_e32 v48, v0
	v_mov_b32_e32 v49, v0
	v_mov_b32_e32 v50, v0
	v_mov_b32_e32 v51, v0
	v_mov_b32_e32 v52, v0
	v_mov_b32_e32 v53, v0
	v_mov_b32_e32 v54, v0
	v_mov_b32_e32 v55, v0
	v_mov_b32_e32 v56, v0
	v_mov_b32_e32 v57, v0
	v_mov_b32_e32 v58, v0
	v_mov_b32_e32 v59, v0
	v_mov_b32_e32 v60, v0
	v_mov_b32_e32 v61, v0
	v_mov_b32_e32 v62, v0
	v_mov_b32_e32 v63, v0
	v_mov_b32_e32 v64, v0
	v_mov_b32_e32 v65, v0
	v_mov_b32_e32 v66, v0
	v_mov_b32_e32 v67, v0
	v_mov_b32_e32 v68, v0
	v_mov_b32_e32 v69, v0
	v_mov_b32_e32 v70, v0
	v_mov_b32_e32 v71, v0
	v_mov_b32_e32 v72, v0
	v_mov_b32_e32 v73, v0
	v_mov_b32_e32 v74, v0
	v_mov_b32_e32 v75, v0
	v_mov_b32_e32 v76, v0
	v_mov_b32_e32 v77, v0
	v_mov_b32_e32 v78, v0
	v_mov_b32_e32 v79, v0
	v_mov_b32_e32 v80, v0
	v_mov_b32_e32 v81, v0
	v_mov_b32_e32 v82, v0
	v_mov_b32_e32 v83, v0
	v_mov_b32_e32 v84, v0
	v_mov_b32_e32 v85, v0
	v_mov_b32_e32 v86, v0
	v_mov_b32_e32 v87, v0
	v_mov_b32_e32 v88, v0
	v_mov_b32_e32 v89, v0
	v_mov_b32_e32 v90, v0
	v_mov_b32_e32 v91, v0
	v_mov_b32_e32 v92, v0
	v_mov_b32_e32 v93, v0
	v_mov_b32_e32 v94, v0
	v_mov_b32_e32 v95, v0
	v_mov_b32_e32 v96, v0
	v_mov_b32_e32 v97, v0
	v_mov_b32_e32 v98, v0
	v_mov_b32_e32 v99, v0
	v_mov_b32_e32 v100, v0
	v_mov_b32_e32 v101, v0
	v_mov_b32_e32 v102, v0
	v_mov_b32_e32 v103, v0
	v_mov_b32_e32 v104, v0
	v_mov_b32_e32 v105, v0
	v_mov_b32_e32 v106, v0
	v_mov_b32_e32 v107, v0
	v_mov_b32_e32 v108, v0
	v_mov_b32_e32 v109, v0
	v_mov_b32_e32 v110, v0
	v_mov_b32_e32 v111, v0
	v_mov_b32_e32 v112, v0
	v_mov_b32_e32 v113, v0
	v_mov_b32_e32 v114, v0
	v_mov_b32_e32 v115, v0
	v_mov_b32_e32 v116, v0
	v_mov_b32_e32 v117, v0
	v_mov_b32_e32 v118, v0
	v_mov_b32_e32 v119, v0
	v_mov_b32_e32 v120, v0
	v_mov_b32_e32 v121, v0
	v_mov_b32_e32 v122, v0
	v_mov_b32_e32 v123, v0
	v_mov_b32_e32 v124, v0
	v_mov_b32_e32 v125, v0
	v_mov_b32_e32 v126, v0
	v_mov_b32_e32 v127, v0
	.p2alignl 6, 3212836864

; __device__ void phaseN2_task(const Params& p, int task, char* lds, bf16_t* ydst, int ystride, volatile unsigned* uex, char* ldsb) {
;     ...
;             if (nbr == 2) break;
;             br = nbr; j = nj;
.LBB0_617:
	s_or_b64 exec, exec, s[6:7]
	v_cmp_eq_u32_e32 vcc, 2, v141
	s_or_b64 s[8:9], vcc, s[8:9]
	v_mov_b32_e32 v102, v97
	v_mov_b32_e32 v103, v88
	v_mov_b32_e32 v143, v141
	v_mov_b32_e32 v56, v142
	s_andn2_b64 exec, exec, s[8:9]
	s_cbranch_execz .LBB0_593
	.p2alignl 6, 3212836864

; #define TIDX512 launder_i((int)threadIdx.x)
; __device__ __forceinline__ void gemm_mainloop(f32x4 (&acc)[8][4], const GemmSrc& g, int K, char* lds) {
;     const int tid = TIDX512, lane = tid & 63, wave = tid >> 6;
;     const int wr = wave >> 2, wc = wave & 3, r = lane & 15, q = lane >> 4;
;     const int KT = K / 64;
;     const int rdo0 = r * 128 + ((q ^ (r >> 1)) * 16), rdo1 = r * 128 + (((4 + q) ^ (r >> 1)) * 16);
;     const int woff = 32768 + wc * 64 * 128, xoff = wr * 128 * 128;
; __device__ __forceinline__ void zero_acc(f32x4 (&acc)[8][4]) {
; #pragma unroll
;     for (int a = 0; a < 8; a++)
; #pragma unroll
;         for (int b = 0; b < 4; b++) acc[a][b] = (f32x4){0.f, 0.f, 0.f, 0.f};
; }
.LBB0_713:
	v_mov_b32_e32 v0, v158
	v_ashrrev_i32_e32 v135, 31, v134
	v_and_b32_e32 v1, 15, v0
	v_lshrrev_b32_e32 v2, 4, v0
	v_bfe_u32 v4, v0, 1, 3
	v_bfe_u32 v3, v0, 4, 2
	v_lshlrev_b32_e32 v1, 7, v1
	v_bitop3_b32 v2, v2, v4, 3 bitop3:0x6c
	v_lshl_or_b32 v142, v2, 4, v1
	v_bitop3_b32 v2, v3, v4, 4 bitop3:0x36
	v_lshl_or_b32 v128, v2, 4, v1
	v_lshlrev_b32_e32 v1, 7, v0
	v_lshlrev_b32_e32 v0, 6, v0
	v_and_b32_e32 v164, 0x6000, v1
	v_and_b32_e32 v143, 0xffffc000, v0
	v_lshl_add_u64 v[132:133], v[132:133], 0, s[22:23]
	v_lshlrev_b64 v[0:1], 1, v[134:135]
	s_lshl_b64 s[0:1], s[56:57], 5
	v_lshl_add_u64 v[2:3], s[56:57], 4, v[0:1]
	v_lshl_add_u64 v[136:137], v[130:131], 0, v[0:1]
	v_lshl_add_u64 v[138:139], v[132:133], 0, s[0:1]
	v_mad_u64_u32 v[0:1], s[0:1], s56, 48, v[0:1]
	v_lshl_add_u64 v[134:135], v[132:133], 0, v[2:3]
	v_mov_b32_e32 v2, v1
	v_mad_u64_u32 v[2:3], s[0:1], s57, 48, v[2:3]
	v_mov_b32_e32 v1, v2
	v_lshl_add_u64 v[140:141], v[132:133], 0, v[0:1]
	v_mov_b32_e32 v0, 0
	s_xor_b64 s[52:53], s[54:55], -1
	s_mov_b64 s[56:57], 0
	s_mov_b32 s0, 0x10000
	v_mov_b32_e32 v1, v0
	v_mov_b32_e32 v2, v0
	v_mov_b32_e32 v3, v0
	v_mov_b32_e32 v4, v0
	v_mov_b32_e32 v5, v0
	v_mov_b32_e32 v6, v0
	v_mov_b32_e32 v7, v0
	v_mov_b32_e32 v8, v0
	v_mov_b32_e32 v9, v0
	v_mov_b32_e32 v10, v0
	v_mov_b32_e32 v11, v0
	v_mov_b32_e32 v12, v0
	v_mov_b32_e32 v13, v0
	v_mov_b32_e32 v14, v0
	v_mov_b32_e32 v15, v0
	v_mov_b32_e32 v16, v0
	v_mov_b32_e32 v17, v0
	v_mov_b32_e32 v18, v0
	v_mov_b32_e32 v19, v0
	v_mov_b32_e32 v20, v0
	v_mov_b32_e32 v21, v0
	v_mov_b32_e32 v22, v0
	v_mov_b32_e32 v23, v0
	v_mov_b32_e32 v24, v0
	v_mov_b32_e32 v25, v0
	v_mov_b32_e32 v26, v0
	v_mov_b32_e32 v27, v0
	v_mov_b32_e32 v28, v0
	v_mov_b32_e32 v29, v0
	v_mov_b32_e32 v30, v0
	v_mov_b32_e32 v31, v0
	v_mov_b32_e32 v32, v0
	v_mov_b32_e32 v33, v0
	v_mov_b32_e32 v34, v0
	v_mov_b32_e32 v35, v0
	v_mov_b32_e32 v36, v0
	v_mov_b32_e32 v37, v0
	v_mov_b32_e32 v38, v0
	v_mov_b32_e32 v39, v0
	v_mov_b32_e32 v40, v0
	v_mov_b32_e32 v41, v0
	v_mov_b32_e32 v42, v0
	v_mov_b32_e32 v43, v0
	v_mov_b32_e32 v44, v0
	v_mov_b32_e32 v45, v0
	v_mov_b32_e32 v46, v0
	v_mov_b32_e32 v47, v0
	v_mov_b32_e32 v48, v0
	v_mov_b32_e32 v49, v0
	v_mov_b32_e32 v50, v0
	v_mov_b32_e32 v51, v0
	v_mov_b32_e32 v52, v0
	v_mov_b32_e32 v53, v0
	v_mov_b32_e32 v54, v0
	v_mov_b32_e32 v55, v0
	v_mov_b32_e32 v56, v0
	v_mov_b32_e32 v57, v0
	v_mov_b32_e32 v58, v0
	v_mov_b32_e32 v59, v0
	v_mov_b32_e32 v60, v0
	v_mov_b32_e32 v61, v0
	v_mov_b32_e32 v62, v0
	v_mov_b32_e32 v63, v0
	v_mov_b32_e32 v64, v0
	v_mov_b32_e32 v65, v0
	v_mov_b32_e32 v66, v0
	v_mov_b32_e32 v67, v0
	v_mov_b32_e32 v68, v0
	v_mov_b32_e32 v69, v0
	v_mov_b32_e32 v70, v0
	v_mov_b32_e32 v71, v0
	v_mov_b32_e32 v72, v0
	v_mov_b32_e32 v73, v0
	v_mov_b32_e32 v74, v0
	v_mov_b32_e32 v75, v0
	v_mov_b32_e32 v76, v0
	v_mov_b32_e32 v77, v0
	v_mov_b32_e32 v78, v0
	v_mov_b32_e32 v79, v0
	v_mov_b32_e32 v80, v0
	v_mov_b32_e32 v81, v0
	v_mov_b32_e32 v82, v0
	v_mov_b32_e32 v83, v0
	v_mov_b32_e32 v84, v0
	v_mov_b32_e32 v85, v0
	v_mov_b32_e32 v86, v0
	v_mov_b32_e32 v87, v0
	v_mov_b32_e32 v88, v0
	v_mov_b32_e32 v89, v0
	v_mov_b32_e32 v90, v0
	v_mov_b32_e32 v91, v0
	v_mov_b32_e32 v92, v0
	v_mov_b32_e32 v93, v0
	v_mov_b32_e32 v94, v0
	v_mov_b32_e32 v95, v0
	v_mov_b32_e32 v96, v0
	v_mov_b32_e32 v97, v0
	v_mov_b32_e32 v98, v0
	v_mov_b32_e32 v99, v0
	v_mov_b32_e32 v100, v0
	v_mov_b32_e32 v101, v0
	v_mov_b32_e32 v102, v0
	v_mov_b32_e32 v103, v0
	v_mov_b32_e32 v104, v0
	v_mov_b32_e32 v105, v0
	v_mov_b32_e32 v106, v0
	v_mov_b32_e32 v107, v0
	v_mov_b32_e32 v108, v0
	v_mov_b32_e32 v109, v0
	v_mov_b32_e32 v110, v0
	v_mov_b32_e32 v111, v0
	v_mov_b32_e32 v112, v0
	v_mov_b32_e32 v113, v0
	v_mov_b32_e32 v114, v0
	v_mov_b32_e32 v115, v0
	v_mov_b32_e32 v116, v0
	v_mov_b32_e32 v117, v0
	v_mov_b32_e32 v118, v0
	v_mov_b32_e32 v119, v0
	v_mov_b32_e32 v120, v0
	v_mov_b32_e32 v121, v0
	v_mov_b32_e32 v122, v0
	v_mov_b32_e32 v123, v0
	v_mov_b32_e32 v124, v0
	v_mov_b32_e32 v125, v0
	v_mov_b32_e32 v126, v0
	v_mov_b32_e32 v127, v0
	.p2alignl 6, 3212836864
.LBB0_714:
	s_add_i32 s1, s0, 0xffff0000
	s_and_b32 s1, s1, 0x10000
	v_or_b32_e32 v165, s1, v164
	v_add_u32_e32 v218, s1, v143
	v_add_u32_e32 v178, v165, v142
	v_add_u32_e32 v202, v218, v142
	v_mov_b32_e32 v198, v158
	s_waitcnt vmcnt(0)
	s_barrier
; #define TIDX512 launder_i((int)threadIdx.x)
; __device__ __forceinline__ void gemm_issue(const GemmSrc& g, int kt, int s, char* lds) {
;     const int tid = TIDX512, lane = tid & 63, wave = tid >> 6;
;     char* xdst = lds + s * 65536 + wave * 4096 + lane * 16;
;     char* wdst = xdst + 32768;
; #pragma unroll
;     for (int i = 0; i < 4; i++) {
;         const int d = (i & 1) ? g.dsw : 0;
; __device__ __forceinline__ void gemm_mainloop(f32x4 (&acc)[8][4], const GemmSrc& g, int K, char* lds) {
;     ...
;     for (int kt = 0; kt < KT; kt++) {
;         WAIT_V(0);
;         __builtin_amdgcn_s_barrier();
;         const char* st = lds + (kt & 1) * 65536;
;         bf16x8 afA[4], afB[4], bX[4], bY[4];
; #pragma unroll
;         for (int ni = 0; ni < 4; ni++) afA[ni] = *(const bf16x8*)(st + woff + ni * 16 * 128 + rdo0);
; #pragma unroll
;         for (int mi = 0; mi < 4; mi++) bX[mi] = *(const bf16x8*)(st + xoff + mi * 16 * 128 + rdo0);
;         if (kt + 1 < KT) gemm_issue(g, kt + 1, (kt + 1) & 1, lds);
; #pragma unroll
;         for (int mi = 0; mi < 4; mi++) bY[mi] = *(const bf16x8*)(st + xoff + (4 + mi) * 16 * 128 + rdo0);
; #pragma unroll
;         for (int ni = 0; ni < 4; ni++) afB[ni] = *(const bf16x8*)(st + woff + ni * 16 * 128 + rdo1);
; #pragma unroll
;         for (int mi = 0; mi < 4; mi++)
; #pragma unroll
;             for (int ni = 0; ni < 4; ni++) acc[mi][ni] = mfma16(afA[ni], bX[mi], acc[mi][ni]);
;         __builtin_amdgcn_sched_barrier(0);
; #pragma unroll
;         for (int mi = 0; mi < 4; mi++) bX[mi] = *(const bf16x8*)(st + xoff + mi * 16 * 128 + rdo1);
; #pragma unroll
;         for (int mi = 0; mi < 4; mi++)
; #pragma unroll
;             for (int ni = 0; ni < 4; ni++) acc[4 + mi][ni] = mfma16(afA[ni], bY[mi], acc[4 + mi][ni]);
;         __builtin_amdgcn_sched_barrier(0);
; #pragma unroll
;         for (int mi = 0; mi < 4; mi++) bY[mi] = *(const bf16x8*)(st + xoff + (4 + mi) * 16 * 128 + rdo1);
; #pragma unroll
;         for (int mi = 0; mi < 4; mi++)
; #pragma unroll
;             for (int ni = 0; ni < 4; ni++) acc[mi][ni] = mfma16(afB[ni], bX[mi], acc[mi][ni]);
;         __builtin_amdgcn_sched_barrier(0);
; #pragma unroll
;         for (int mi = 0; mi < 4; mi++)
; #pragma unroll
;             for (int ni = 0; ni < 4; ni++) acc[4 + mi][ni] = mfma16(afB[ni], bY[mi], acc[4 + mi][ni]);
;         __builtin_amdgcn_sched_barrier(0);
;     }
	ds_read_b128 v[166:169], v178 offset:32768
	ds_read_b128 v[170:173], v178 offset:34816
	ds_read_b128 v[174:177], v178 offset:36864
	ds_read_b128 v[178:181], v178 offset:38912
	ds_read_b128 v[182:185], v202
	ds_read_b128 v[186:189], v202 offset:2048
	ds_read_b128 v[190:193], v202 offset:4096
	ds_read_b128 v[194:197], v202 offset:6144
	s_and_b32 s1, s0, 0x10000
	v_lshlrev_b32_e32 v199, 6, v198
	v_and_b32_e32 v199, 0xfffff000, v199
	v_add_u32_e32 v199, s1, v199
	v_lshlrev_b32_e32 v198, 4, v198
	v_and_or_b32 v203, v198, s64, v199
	v_add_u32_e32 v204, 0x8000, v203
	v_readfirstlane_b32 s1, v203
	v_lshl_add_u64 v[198:199], v[132:133], 0, s[56:57]
	s_mov_b32 m0, s1
	v_readfirstlane_b32 s1, v204
	global_load_lds_dwordx4 v[198:199], off
	v_lshl_add_u64 v[198:199], v[130:131], 0, s[56:57]
	v_or_b32_e32 v204, 0x400, v203
	v_lshl_add_u64 v[200:201], v[198:199], 0, s[22:23]
	s_mov_b32 m0, s1
	v_readfirstlane_b32 s1, v204
	s_waitcnt lgkmcnt(0)
	v_mfma_f32_16x16x32_bf16 v[124:127], v[166:169], v[182:185], v[124:127]
	global_load_lds_dwordx4 v[200:201], off
	v_lshl_add_u64 v[200:201], v[134:135], 0, s[56:57]
	v_mfma_f32_16x16x32_bf16 v[120:123], v[170:173], v[182:185], v[120:123]
	s_mov_b32 m0, s1
	v_add_u32_e32 v165, v165, v128
	global_load_lds_dwordx4 v[200:201], off
	v_mfma_f32_16x16x32_bf16 v[116:119], v[174:177], v[182:185], v[116:119]
	v_lshl_add_u64 v[200:201], v[136:137], 0, s[56:57]
	v_mfma_f32_16x16x32_bf16 v[112:115], v[178:181], v[182:185], v[112:115]
	v_add_u32_e32 v184, 0x8400, v203
	v_lshl_add_u64 v[182:183], v[200:201], 0, s[24:25]
	v_readfirstlane_b32 s1, v184
	v_or_b32_e32 v184, 0x800, v203
	s_mov_b32 m0, s1
	v_readfirstlane_b32 s1, v184
	v_add_u32_e32 v184, 0x8800, v203
	global_load_lds_dwordx4 v[182:183], off
	v_lshl_add_u64 v[182:183], v[138:139], 0, s[56:57]
	s_mov_b32 m0, s1
	v_readfirstlane_b32 s1, v184
	v_or_b32_e32 v184, 0xc00, v203
	global_load_lds_dwordx4 v[182:183], off
	v_lshl_add_u64 v[182:183], v[198:199], 0, s[26:27]
	s_mov_b32 m0, s1
	v_readfirstlane_b32 s1, v184
	v_add_u32_e32 v184, 0x8c00, v203
	global_load_lds_dwordx4 v[182:183], off
	v_lshl_add_u64 v[182:183], v[140:141], 0, s[56:57]
	s_mov_b32 m0, s1
	v_readfirstlane_b32 s1, v184
	global_load_lds_dwordx4 v[182:183], off
	v_lshl_add_u64 v[182:183], v[200:201], 0, s[28:29]
	s_mov_b32 m0, s1
	v_mfma_f32_16x16x32_bf16 v[108:111], v[166:169], v[186:189], v[108:111]
	global_load_lds_dwordx4 v[182:183], off
	v_mfma_f32_16x16x32_bf16 v[104:107], v[170:173], v[186:189], v[104:107]
	v_mfma_f32_16x16x32_bf16 v[100:103], v[174:177], v[186:189], v[100:103]
	v_mfma_f32_16x16x32_bf16 v[96:99], v[178:181], v[186:189], v[96:99]
	ds_read_b128 v[182:185], v202 offset:8192
	ds_read_b128 v[186:189], v202 offset:10240
	v_mfma_f32_16x16x32_bf16 v[92:95], v[166:169], v[190:193], v[92:95]
	v_mfma_f32_16x16x32_bf16 v[88:91], v[170:173], v[190:193], v[88:91]
	v_mfma_f32_16x16x32_bf16 v[84:87], v[174:177], v[190:193], v[84:87]
	v_mfma_f32_16x16x32_bf16 v[80:83], v[178:181], v[190:193], v[80:83]
	ds_read_b128 v[190:193], v202 offset:12288
	ds_read_b128 v[198:201], v202 offset:14336
	ds_read_b128 v[202:205], v165 offset:32768
	ds_read_b128 v[206:209], v165 offset:34816
	ds_read_b128 v[210:213], v165 offset:36864
	ds_read_b128 v[214:217], v165 offset:38912
	v_mfma_f32_16x16x32_bf16 v[76:79], v[166:169], v[194:197], v[76:79]
	v_mfma_f32_16x16x32_bf16 v[72:75], v[170:173], v[194:197], v[72:75]
	v_mfma_f32_16x16x32_bf16 v[68:71], v[174:177], v[194:197], v[68:71]
	v_mfma_f32_16x16x32_bf16 v[64:67], v[178:181], v[194:197], v[64:67]
	v_add_u32_e32 v165, v218, v128
	s_waitcnt lgkmcnt(0)
	v_mfma_f32_16x16x32_bf16 v[60:63], v[166:169], v[182:185], v[60:63]
	v_mfma_f32_16x16x32_bf16 v[56:59], v[170:173], v[182:185], v[56:59]
	v_mfma_f32_16x16x32_bf16 v[52:55], v[174:177], v[182:185], v[52:55]
	v_mfma_f32_16x16x32_bf16 v[48:51], v[178:181], v[182:185], v[48:51]
	v_mfma_f32_16x16x32_bf16 v[44:47], v[166:169], v[186:189], v[44:47]
	v_mfma_f32_16x16x32_bf16 v[40:43], v[170:173], v[186:189], v[40:43]
	v_mfma_f32_16x16x32_bf16 v[36:39], v[174:177], v[186:189], v[36:39]
	v_mfma_f32_16x16x32_bf16 v[28:31], v[166:169], v[190:193], v[28:31]
	v_mfma_f32_16x16x32_bf16 v[24:27], v[170:173], v[190:193], v[24:27]
	v_mfma_f32_16x16x32_bf16 v[20:23], v[174:177], v[190:193], v[20:23]
	v_mfma_f32_16x16x32_bf16 v[12:15], v[166:169], v[198:201], v[12:15]
	v_mfma_f32_16x16x32_bf16 v[8:11], v[170:173], v[198:201], v[8:11]
	v_mfma_f32_16x16x32_bf16 v[4:7], v[174:177], v[198:201], v[4:7]
	ds_read_b128 v[166:169], v165
	ds_read_b128 v[170:173], v165 offset:2048
	ds_read_b128 v[174:177], v165 offset:4096
	ds_read_b128 v[182:185], v165 offset:6144
	v_mfma_f32_16x16x32_bf16 v[32:35], v[178:181], v[186:189], v[32:35]
	v_mfma_f32_16x16x32_bf16 v[16:19], v[178:181], v[190:193], v[16:19]
	v_mfma_f32_16x16x32_bf16 v[0:3], v[178:181], v[198:201], v[0:3]
	s_waitcnt lgkmcnt(0)
	v_mfma_f32_16x16x32_bf16 v[124:127], v[202:205], v[166:169], v[124:127]
	v_mfma_f32_16x16x32_bf16 v[120:123], v[206:209], v[166:169], v[120:123]
	v_mfma_f32_16x16x32_bf16 v[116:119], v[210:213], v[166:169], v[116:119]
	v_mfma_f32_16x16x32_bf16 v[112:115], v[214:217], v[166:169], v[112:115]
	v_mfma_f32_16x16x32_bf16 v[108:111], v[202:205], v[170:173], v[108:111]
	v_mfma_f32_16x16x32_bf16 v[104:107], v[206:209], v[170:173], v[104:107]
	v_mfma_f32_16x16x32_bf16 v[100:103], v[210:213], v[170:173], v[100:103]
	v_mfma_f32_16x16x32_bf16 v[96:99], v[214:217], v[170:173], v[96:99]
	v_mfma_f32_16x16x32_bf16 v[92:95], v[202:205], v[174:177], v[92:95]
	v_mfma_f32_16x16x32_bf16 v[88:91], v[206:209], v[174:177], v[88:91]
	v_mfma_f32_16x16x32_bf16 v[84:87], v[210:213], v[174:177], v[84:87]
	v_mfma_f32_16x16x32_bf16 v[80:83], v[214:217], v[174:177], v[80:83]
	ds_read_b128 v[166:169], v165 offset:8192
	ds_read_b128 v[170:173], v165 offset:10240
	ds_read_b128 v[174:177], v165 offset:12288
	ds_read_b128 v[178:181], v165 offset:14336
	v_mfma_f32_16x16x32_bf16 v[76:79], v[202:205], v[182:185], v[76:79]
	v_mfma_f32_16x16x32_bf16 v[72:75], v[206:209], v[182:185], v[72:75]
	v_mfma_f32_16x16x32_bf16 v[68:71], v[210:213], v[182:185], v[68:71]
	v_mfma_f32_16x16x32_bf16 v[64:67], v[214:217], v[182:185], v[64:67]
	s_waitcnt lgkmcnt(0)
; __device__ __forceinline__ f32x4 mfma16(bf16x8 a, bf16x8 b, f32x4 c) { return __builtin_amdgcn_mfma_f32_16x16x32_bf16(a, b, c, 0, 0, 0); }
; #define WAIT_V(n) asm volatile("s_waitcnt vmcnt(" #n ")" ::: "memory")
; __device__ __forceinline__ void gemm_mainloop(f32x4 (&acc)[8][4], const GemmSrc& g, int K, char* lds) {
;     ...
;     for (int kt = 0; kt < KT; kt++) {
;         WAIT_V(0);
;         __builtin_amdgcn_s_barrier();
;         const char* st = lds + (kt & 1) * 65536;
;         bf16x8 afA[4], afB[4], bX[4], bY[4];
; #pragma unroll
;         for (int ni = 0; ni < 4; ni++) afA[ni] = *(const bf16x8*)(st + woff + ni * 16 * 128 + rdo0);
; #pragma unroll
;         for (int mi = 0; mi < 4; mi++) bX[mi] = *(const bf16x8*)(st + xoff + mi * 16 * 128 + rdo0);
;         if (kt + 1 < KT) gemm_issue(g, kt + 1, (kt + 1) & 1, lds);
; #pragma unroll
;         for (int mi = 0; mi < 4; mi++) bY[mi] = *(const bf16x8*)(st + xoff + (4 + mi) * 16 * 128 + rdo0);
; #pragma unroll
;         for (int ni = 0; ni < 4; ni++) afB[ni] = *(const bf16x8*)(st + woff + ni * 16 * 128 + rdo1);
; #pragma unroll
;         for (int mi = 0; mi < 4; mi++)
; #pragma unroll
;             for (int ni = 0; ni < 4; ni++) acc[mi][ni] = mfma16(afA[ni], bX[mi], acc[mi][ni]);
;         __builtin_amdgcn_sched_barrier(0);
; #pragma unroll
;         for (int mi = 0; mi < 4; mi++) bX[mi] = *(const bf16x8*)(st + xoff + mi * 16 * 128 + rdo1);
; #pragma unroll
;         for (int mi = 0; mi < 4; mi++)
; #pragma unroll
;             for (int ni = 0; ni < 4; ni++) acc[4 + mi][ni] = mfma16(afA[ni], bY[mi], acc[4 + mi][ni]);
;         __builtin_amdgcn_sched_barrier(0);
; #pragma unroll
;         for (int mi = 0; mi < 4; mi++) bY[mi] = *(const bf16x8*)(st + xoff + (4 + mi) * 16 * 128 + rdo1);
; #pragma unroll
;         for (int mi = 0; mi < 4; mi++)
; #pragma unroll
;             for (int ni = 0; ni < 4; ni++) acc[mi][ni] = mfma16(afB[ni], bX[mi], acc[mi][ni]);
;         __builtin_amdgcn_sched_barrier(0);
; #pragma unroll
;         for (int mi = 0; mi < 4; mi++)
; #pragma unroll
;             for (int ni = 0; ni < 4; ni++) acc[4 + mi][ni] = mfma16(afB[ni], bY[mi], acc[4 + mi][ni]);
;         __builtin_amdgcn_sched_barrier(0);
;     }
	v_mfma_f32_16x16x32_bf16 v[60:63], v[202:205], v[166:169], v[60:63]
	v_mfma_f32_16x16x32_bf16 v[56:59], v[206:209], v[166:169], v[56:59]
	v_mfma_f32_16x16x32_bf16 v[52:55], v[210:213], v[166:169], v[52:55]
	v_mfma_f32_16x16x32_bf16 v[48:51], v[214:217], v[166:169], v[48:51]
	v_mfma_f32_16x16x32_bf16 v[44:47], v[202:205], v[170:173], v[44:47]
	v_mfma_f32_16x16x32_bf16 v[40:43], v[206:209], v[170:173], v[40:43]
	v_mfma_f32_16x16x32_bf16 v[36:39], v[210:213], v[170:173], v[36:39]
	v_mfma_f32_16x16x32_bf16 v[32:35], v[214:217], v[170:173], v[32:35]
	v_mfma_f32_16x16x32_bf16 v[28:31], v[202:205], v[174:177], v[28:31]
	v_mfma_f32_16x16x32_bf16 v[24:27], v[206:209], v[174:177], v[24:27]
	v_mfma_f32_16x16x32_bf16 v[20:23], v[210:213], v[174:177], v[20:23]
	v_mfma_f32_16x16x32_bf16 v[16:19], v[214:217], v[174:177], v[16:19]
	v_mfma_f32_16x16x32_bf16 v[12:15], v[202:205], v[178:181], v[12:15]
	v_mfma_f32_16x16x32_bf16 v[8:11], v[206:209], v[178:181], v[8:11]
	v_mfma_f32_16x16x32_bf16 v[4:7], v[210:213], v[178:181], v[4:7]
	v_mfma_f32_16x16x32_bf16 v[0:3], v[214:217], v[178:181], v[0:3]
	s_add_u32 s56, s56, 0x80
	s_addc_u32 s57, s57, 0
	s_add_i32 s0, s0, 0x10000
	s_cmpk_lg_i32 s56, 0x780
	s_cbranch_scc1 .LBB0_714
	v_or_b32_e32 v176, 0x8000, v164
	s_mov_b32 s0, 0x10000
	v_add_u32_e32 v143, 0x10000, v143
	v_add3_u32 v172, v176, v142, s0
	v_add_u32_e32 v142, v143, v142
	s_waitcnt vmcnt(0)
	s_barrier
	ds_read_b128 v[130:133], v172
	ds_read_b128 v[134:137], v172 offset:2048
	ds_read_b128 v[138:141], v142
	ds_read_b128 v[164:167], v142 offset:2048
	ds_read_b128 v[168:171], v172 offset:4096
	ds_read_b128 v[172:175], v172 offset:6144
	s_waitcnt lgkmcnt(0)
	v_mfma_f32_16x16x32_bf16 v[124:127], v[130:133], v[138:141], v[124:127]
	v_add3_u32 v184, v176, v128, s0
	v_mfma_f32_16x16x32_bf16 v[120:123], v[134:137], v[138:141], v[120:123]
	v_mfma_f32_16x16x32_bf16 v[116:119], v[168:171], v[138:141], v[116:119]
	v_mfma_f32_16x16x32_bf16 v[112:115], v[172:175], v[138:141], v[112:115]
	v_mfma_f32_16x16x32_bf16 v[108:111], v[130:133], v[164:167], v[108:111]
	v_mfma_f32_16x16x32_bf16 v[104:107], v[134:137], v[164:167], v[104:107]
	v_mfma_f32_16x16x32_bf16 v[100:103], v[168:171], v[164:167], v[100:103]
	v_mfma_f32_16x16x32_bf16 v[96:99], v[172:175], v[164:167], v[96:99]
	ds_read_b128 v[138:141], v142 offset:4096
	ds_read_b128 v[164:167], v142 offset:6144
	s_waitcnt lgkmcnt(0)
	v_mfma_f32_16x16x32_bf16 v[92:95], v[130:133], v[138:141], v[92:95]
	v_mfma_f32_16x16x32_bf16 v[88:91], v[134:137], v[138:141], v[88:91]
	v_mfma_f32_16x16x32_bf16 v[84:87], v[168:171], v[138:141], v[84:87]
	v_mfma_f32_16x16x32_bf16 v[80:83], v[172:175], v[138:141], v[80:83]
	ds_read_b128 v[138:141], v184 offset:6144
	ds_read_b128 v[176:179], v184 offset:4096
	ds_read_b128 v[180:183], v184 offset:2048
	ds_read_b128 v[184:187], v184
	ds_read_b128 v[188:191], v142 offset:14336
	ds_read_b128 v[192:195], v142 offset:12288
	ds_read_b128 v[196:199], v142 offset:10240
	ds_read_b128 v[200:203], v142 offset:8192
	v_mfma_f32_16x16x32_bf16 v[76:79], v[130:133], v[164:167], v[76:79]
	v_mfma_f32_16x16x32_bf16 v[72:75], v[134:137], v[164:167], v[72:75]
	v_mfma_f32_16x16x32_bf16 v[68:71], v[168:171], v[164:167], v[68:71]
	v_mfma_f32_16x16x32_bf16 v[64:67], v[172:175], v[164:167], v[64:67]
	v_add_u32_e32 v128, v143, v128
	s_waitcnt lgkmcnt(0)
	v_mfma_f32_16x16x32_bf16 v[60:63], v[130:133], v[200:203], v[60:63]
	v_mfma_f32_16x16x32_bf16 v[56:59], v[134:137], v[200:203], v[56:59]
	v_mfma_f32_16x16x32_bf16 v[52:55], v[168:171], v[200:203], v[52:55]
	v_mfma_f32_16x16x32_bf16 v[44:47], v[130:133], v[196:199], v[44:47]
	v_mfma_f32_16x16x32_bf16 v[40:43], v[134:137], v[196:199], v[40:43]
	v_mfma_f32_16x16x32_bf16 v[36:39], v[168:171], v[196:199], v[36:39]
	v_mfma_f32_16x16x32_bf16 v[28:31], v[130:133], v[192:195], v[28:31]
	v_mfma_f32_16x16x32_bf16 v[24:27], v[134:137], v[192:195], v[24:27]
	v_mfma_f32_16x16x32_bf16 v[20:23], v[168:171], v[192:195], v[20:23]
	v_mfma_f32_16x16x32_bf16 v[12:15], v[130:133], v[188:191], v[12:15]
	v_mfma_f32_16x16x32_bf16 v[8:11], v[134:137], v[188:191], v[8:11]
	v_mfma_f32_16x16x32_bf16 v[4:7], v[168:171], v[188:191], v[4:7]
	ds_read_b128 v[130:133], v128
	ds_read_b128 v[134:137], v128 offset:2048
	ds_read_b128 v[164:167], v128 offset:4096
	ds_read_b128 v[168:171], v128 offset:6144
	v_mfma_f32_16x16x32_bf16 v[48:51], v[172:175], v[200:203], v[48:51]
	v_mfma_f32_16x16x32_bf16 v[32:35], v[172:175], v[196:199], v[32:35]
	v_mfma_f32_16x16x32_bf16 v[16:19], v[172:175], v[192:195], v[16:19]
	v_mfma_f32_16x16x32_bf16 v[0:3], v[172:175], v[188:191], v[0:3]
	s_waitcnt lgkmcnt(0)
	v_mfma_f32_16x16x32_bf16 v[124:127], v[184:187], v[130:133], v[124:127]
	v_mfma_f32_16x16x32_bf16 v[120:123], v[180:183], v[130:133], v[120:123]
	v_mfma_f32_16x16x32_bf16 v[116:119], v[176:179], v[130:133], v[116:119]
	v_mfma_f32_16x16x32_bf16 v[172:175], v[138:141], v[130:133], v[112:115]
	v_mfma_f32_16x16x32_bf16 v[108:111], v[184:187], v[134:137], v[108:111]
	v_mfma_f32_16x16x32_bf16 v[104:107], v[180:183], v[134:137], v[104:107]
	v_mfma_f32_16x16x32_bf16 v[100:103], v[176:179], v[134:137], v[100:103]
	v_mfma_f32_16x16x32_bf16 v[96:99], v[138:141], v[134:137], v[96:99]
	v_mfma_f32_16x16x32_bf16 v[92:95], v[184:187], v[164:167], v[92:95]
	v_mfma_f32_16x16x32_bf16 v[88:91], v[180:183], v[164:167], v[88:91]
	v_mfma_f32_16x16x32_bf16 v[84:87], v[176:179], v[164:167], v[84:87]
	v_mfma_f32_16x16x32_bf16 v[80:83], v[138:141], v[164:167], v[80:83]
	ds_read_b128 v[112:115], v128 offset:8192
	ds_read_b128 v[130:133], v128 offset:10240
	ds_read_b128 v[134:137], v128 offset:12288
	ds_read_b128 v[164:167], v128 offset:14336
	v_mfma_f32_16x16x32_bf16 v[76:79], v[184:187], v[168:171], v[76:79]
	v_mfma_f32_16x16x32_bf16 v[72:75], v[180:183], v[168:171], v[72:75]
	v_mfma_f32_16x16x32_bf16 v[68:71], v[176:179], v[168:171], v[68:71]
	v_mfma_f32_16x16x32_bf16 v[64:67], v[138:141], v[168:171], v[64:67]
	s_waitcnt lgkmcnt(0)
; __device__ __forceinline__ int launder_i(int x) { asm volatile("" : "+v"(x)); return x; }
; #define TIDX512 launder_i((int)threadIdx.x)
; __device__ __forceinline__ float sigmoidf_(float x) { return __builtin_amdgcn_rcpf(1.f + __expf(-x)); }
; __device__ __forceinline__ void glds16(const bf16_t* g, char* l) { __builtin_amdgcn_global_load_lds((const unsigned*)g, (unsigned*)l, 16, 0, 0); }
; __device__ __forceinline__ void gemm_prologue(const GemmSrc& g, char* lds) { gemm_issue(g, 0, 0, lds); }
; __device__ __forceinline__ void gemm_issue(const GemmSrc& g, int kt, int s, char* lds) {
;     const int tid = TIDX512, lane = tid & 63, wave = tid >> 6;
;     char* xdst = lds + s * 65536 + wave * 4096 + lane * 16;
;     char* wdst = xdst + 32768;
; #pragma unroll
;     for (int i = 0; i < 4; i++) {
;         const int d = (i & 1) ? g.dsw : 0;
;         glds16(g.xsrc + (size_t)i * 8 * g.ldx + kt * 64 + d, xdst + i * 1024);
;         glds16(g.wsrc + (size_t)i * 8 * g.ldw + kt * 64 + d, wdst + i * 1024);
;     }
; __device__ void phaseM1(const Params& p, char* lds) {
;     ...
;             __syncthreads();
;             g = gemm_src(Z + (br ? ZQ_N : ZR_G), ZC, (const bf16_t*)(p.ws + (br ? OFF_WB : OFF_WA)), DM, m0, n0);
;             gemm_prologue(g, lds);
;             {
; #pragma unroll
;                 for (int mi = 0; mi < 8; mi++)
; #pragma unroll
;                     for (int nh = 0; nh < 2; nh++) {
;                         const f32x4 a0 = acc[mi][2 * nh], a1 = acc[mi][2 * nh + 1];
;                         SG[(size_t)launder_i(pbase + (mi * 2 + nh) * 512)] = (u32x4){pack2(sigmoidf_(a0[0]), sigmoidf_(a0[1])), pack2(sigmoidf_(a0[2]), sigmoidf_(a0[3])),
;                                                                           pack2(sigmoidf_(a1[0]), sigmoidf_(a1[1])), pack2(sigmoidf_(a1[2]), sigmoidf_(a1[3]))};
;                     }
	v_mfma_f32_16x16x32_bf16 v[60:63], v[184:187], v[112:115], v[60:63]
	v_mfma_f32_16x16x32_bf16 v[56:59], v[180:183], v[112:115], v[56:59]
	v_mfma_f32_16x16x32_bf16 v[52:55], v[176:179], v[112:115], v[52:55]
	v_mfma_f32_16x16x32_bf16 v[48:51], v[138:141], v[112:115], v[48:51]
	v_mfma_f32_16x16x32_bf16 v[44:47], v[184:187], v[130:133], v[44:47]
	v_mfma_f32_16x16x32_bf16 v[40:43], v[180:183], v[130:133], v[40:43]
	v_mfma_f32_16x16x32_bf16 v[36:39], v[176:179], v[130:133], v[36:39]
	v_mfma_f32_16x16x32_bf16 v[32:35], v[138:141], v[130:133], v[32:35]
	v_mfma_f32_16x16x32_bf16 v[28:31], v[184:187], v[134:137], v[28:31]
	v_mfma_f32_16x16x32_bf16 v[24:27], v[180:183], v[134:137], v[24:27]
	v_mfma_f32_16x16x32_bf16 v[20:23], v[176:179], v[134:137], v[20:23]
	v_mfma_f32_16x16x32_bf16 v[16:19], v[138:141], v[134:137], v[16:19]
	v_mfma_f32_16x16x32_bf16 v[12:15], v[184:187], v[164:167], v[12:15]
	v_mfma_f32_16x16x32_bf16 v[8:11], v[180:183], v[164:167], v[8:11]
	v_mfma_f32_16x16x32_bf16 v[4:7], v[176:179], v[164:167], v[4:7]
	v_mfma_f32_16x16x32_bf16 v[0:3], v[138:141], v[164:167], v[0:3]
	s_and_b64 s[2:3], s[54:55], exec
	v_mov_b32_e32 v112, v158
	s_waitcnt vmcnt(0)
	s_barrier
	s_cselect_b32 s30, 0x1000, s67
	s_add_u32 s2, s58, s30
	v_ashrrev_i32_e32 v113, 1, v112
	v_and_b32_e32 v114, 0xffffffe0, v113
	v_bfe_u32 v115, v112, 3, 3
	s_addc_u32 s3, s59, 0
	v_or_b32_e32 v130, v114, v115
	v_bfe_u32 v113, v112, 4, 2
	v_and_b32_e32 v128, 7, v112
	v_bitop3_b32 v134, v113, v112, 7 bitop3:0x78
	v_bitop3_b32 v135, v113, v128, 4 bitop3:0x36
	v_add_u32_e32 v128, s74, v130
	v_mov_b64_e32 v[112:113], s[2:3]
	s_and_b64 s[54:55], s[54:55], exec
	v_mad_i64_i32 v[112:113], s[2:3], v128, s70, v[112:113]
	v_lshlrev_b32_e32 v128, 4, v134
	s_cselect_b32 s54, s69, 0x13c0000
	v_lshl_add_u64 v[132:133], v[112:113], 0, v[128:129]
	v_add_u32_e32 v112, s48, v130
	s_add_u32 s56, s6, s54
	v_ashrrev_i32_e32 v113, 31, v112
	s_addc_u32 s57, s7, 0
	v_lshlrev_b64 v[112:113], 11, v[112:113]
	v_lshl_add_u64 v[112:113], s[56:57], 0, v[112:113]
	v_lshl_add_u64 v[130:131], v[112:113], 0, v[128:129]
	v_sub_u32_e32 v112, v135, v134
	v_lshlrev_b32_e32 v134, 3, v112
	v_mov_b32_e32 v112, v158
	v_ashrrev_i32_e32 v135, 31, v134
	v_lshlrev_b32_e32 v113, 6, v112
	v_lshlrev_b32_e32 v112, 4, v112
	v_and_b32_e32 v112, 0x3f0, v112
	v_and_or_b32 v142, v113, s65, v112
	v_add_u32_e32 v112, 0x8000, v142
	v_readfirstlane_b32 s1, v142
	s_mov_b32 m0, s1
	v_readfirstlane_b32 s1, v112
	v_lshlrev_b64 v[112:113], 1, v[134:135]
	v_or_b32_e32 v135, 0x400, v142
	global_load_lds_dwordx4 v[132:133], off
	s_mov_b32 m0, s1
	v_lshl_add_u64 v[136:137], v[132:133], 0, v[112:113]
	v_readfirstlane_b32 s1, v135
	v_mul_f32_e32 v120, 0xbfb8aa3b, v120
	global_load_lds_dwordx4 v[130:131], off
	v_lshl_add_u64 v[138:139], v[136:137], 0, s[34:35]
	s_mov_b32 m0, s1
	v_add_u32_e32 v135, 0x8400, v142
	v_exp_f32_e32 v120, v120
	v_mul_f32_e32 v121, 0xbfb8aa3b, v121
	global_load_lds_dwordx4 v[138:139], off
	v_lshl_add_u64 v[138:139], v[130:131], 0, v[112:113]
	v_readfirstlane_b32 s1, v135
	v_or_b32_e32 v135, 0x800, v142
	v_exp_f32_e32 v121, v121
	v_lshl_add_u64 v[140:141], v[138:139], 0, s[16:17]
	s_mov_b32 m0, s1
	v_readfirstlane_b32 s1, v135
	v_add_u32_e32 v135, 0x8800, v142
	global_load_lds_dwordx4 v[140:141], off
	v_lshl_add_u64 v[140:141], v[132:133], 0, s[36:37]
	s_mov_b32 m0, s1
	v_readfirstlane_b32 s1, v135
	v_or_b32_e32 v135, 0xc00, v142
	global_load_lds_dwordx4 v[140:141], off
	v_lshl_add_u64 v[140:141], v[130:131], 0, s[18:19]
	s_mov_b32 m0, s1
	v_readfirstlane_b32 s1, v135
	v_add_u32_e32 v135, 0x8c00, v142
	v_mul_f32_e32 v124, 0xbfb8aa3b, v124
	v_mul_f32_e32 v125, 0xbfb8aa3b, v125
	v_add_f32_e32 v120, 1.0, v120
	global_load_lds_dwordx4 v[140:141], off
	s_mov_b32 m0, s1
	v_readfirstlane_b32 s1, v135
	v_exp_f32_e32 v124, v124
	v_exp_f32_e32 v125, v125
	v_rcp_f32_e32 v135, v120
	v_add_f32_e32 v120, 1.0, v121
	v_mul_f32_e32 v121, 0xbfb8aa3b, v122
	v_mul_f32_e32 v126, 0xbfb8aa3b, v126
	v_mul_f32_e32 v127, 0xbfb8aa3b, v127
	v_exp_f32_e32 v121, v121
	v_mul_f32_e32 v122, 0xbfb8aa3b, v123
	v_exp_f32_e32 v126, v126
	v_exp_f32_e32 v127, v127
	v_exp_f32_e32 v122, v122
	v_lshl_add_u64 v[136:137], v[136:137], 0, s[38:39]
	v_add_f32_e32 v124, 1.0, v124
	v_add_f32_e32 v125, 1.0, v125
	global_load_lds_dwordx4 v[136:137], off
	v_lshl_add_u64 v[136:137], v[138:139], 0, s[20:21]
	s_mov_b32 m0, s1
	v_rcp_f32_e32 v124, v124
	v_rcp_f32_e32 v125, v125
	v_rcp_f32_e32 v123, v120
	v_add_f32_e32 v120, 1.0, v121
	global_load_lds_dwordx4 v[136:137], off
	v_add_f32_e32 v126, 1.0, v126
	v_add_f32_e32 v127, 1.0, v127
	v_rcp_f32_e32 v136, v120
	v_add_f32_e32 v120, 1.0, v122
	v_rcp_f32_e32 v126, v126
	v_rcp_f32_e32 v127, v127
	v_rcp_f32_e32 v137, v120
	v_cvt_pk_bf16_f32 v120, v124, v125
	v_mov_b32_e32 v124, v146
	v_cvt_pk_bf16_f32 v121, v126, v127
	v_ashrrev_i32_e32 v125, 31, v124
	v_cvt_pk_bf16_f32 v122, v135, v123
	v_cvt_pk_bf16_f32 v123, v136, v137
	v_lshl_add_u64 v[124:125], v[124:125], 4, s[4:5]
	v_mul_f32_e32 v116, 0xbfb8aa3b, v116
	v_mul_f32_e32 v117, 0xbfb8aa3b, v117
	global_store_dwordx4 v[124:125], v[120:123], off
	v_mul_f32_e32 v118, 0xbfb8aa3b, v118
	v_mul_f32_e32 v119, 0xbfb8aa3b, v119
	v_mul_f32_e32 v120, 0xbfb8aa3b, v172
	v_mul_f32_e32 v121, 0xbfb8aa3b, v173
	v_exp_f32_e32 v116, v116
	v_exp_f32_e32 v117, v117
	v_exp_f32_e32 v118, v118
	v_exp_f32_e32 v119, v119
	v_exp_f32_e32 v120, v120
	v_exp_f32_e32 v121, v121
	v_mul_f32_e32 v122, 0xbfb8aa3b, v174
	v_mul_f32_e32 v123, 0xbfb8aa3b, v175
	v_exp_f32_e32 v122, v122
	v_exp_f32_e32 v123, v123
	v_add_f32_e32 v116, 1.0, v116
	v_add_f32_e32 v117, 1.0, v117
	v_add_f32_e32 v118, 1.0, v118
; __device__ __forceinline__ int launder_i(int x) { asm volatile("" : "+v"(x)); return x; }
; __device__ __forceinline__ float sigmoidf_(float x) { return __builtin_amdgcn_rcpf(1.f + __expf(-x)); }
; __device__ void phaseM1(const Params& p, char* lds) {
;     ...
;             {
; #pragma unroll
;                 for (int mi = 0; mi < 8; mi++)
; #pragma unroll
;                     for (int nh = 0; nh < 2; nh++) {
;                         const f32x4 a0 = acc[mi][2 * nh], a1 = acc[mi][2 * nh + 1];
;                         SG[(size_t)launder_i(pbase + (mi * 2 + nh) * 512)] = (u32x4){pack2(sigmoidf_(a0[0]), sigmoidf_(a0[1])), pack2(sigmoidf_(a0[2]), sigmoidf_(a0[3])),
;                                                                           pack2(sigmoidf_(a1[0]), sigmoidf_(a1[1])), pack2(sigmoidf_(a1[2]), sigmoidf_(a1[3]))};
;                     }
	v_add_f32_e32 v119, 1.0, v119
	v_add_f32_e32 v120, 1.0, v120
	v_add_f32_e32 v121, 1.0, v121
	v_rcp_f32_e32 v116, v116
	v_rcp_f32_e32 v117, v117
	v_rcp_f32_e32 v118, v118
	v_rcp_f32_e32 v119, v119
	v_rcp_f32_e32 v120, v120
	v_rcp_f32_e32 v121, v121
	v_add_f32_e32 v122, 1.0, v122
	v_add_f32_e32 v123, 1.0, v123
	v_mul_f32_e32 v104, 0xbfb8aa3b, v104
	v_rcp_f32_e32 v122, v122
	v_rcp_f32_e32 v123, v123
	v_exp_f32_e32 v104, v104
	v_mul_f32_e32 v105, 0xbfb8aa3b, v105
	v_exp_f32_e32 v105, v105
	v_cvt_pk_bf16_f32 v116, v116, v117
	v_cvt_pk_bf16_f32 v117, v118, v119
	v_cvt_pk_bf16_f32 v118, v120, v121
	v_mov_b32_e32 v120, v147
	v_cvt_pk_bf16_f32 v119, v122, v123
	v_ashrrev_i32_e32 v121, 31, v120
	v_lshl_add_u64 v[120:121], v[120:121], 4, s[4:5]
	v_mul_f32_e32 v108, 0xbfb8aa3b, v108
	v_mul_f32_e32 v109, 0xbfb8aa3b, v109
	v_add_f32_e32 v104, 1.0, v104
	v_exp_f32_e32 v108, v108
	v_exp_f32_e32 v109, v109
	global_store_dwordx4 v[120:121], v[116:119], off
	v_mul_f32_e32 v110, 0xbfb8aa3b, v110
	v_mul_f32_e32 v111, 0xbfb8aa3b, v111
	v_rcp_f32_e32 v116, v104
	v_add_f32_e32 v104, 1.0, v105
	v_mul_f32_e32 v105, 0xbfb8aa3b, v106
	v_exp_f32_e32 v105, v105
	v_mul_f32_e32 v106, 0xbfb8aa3b, v107
	v_exp_f32_e32 v110, v110
	v_exp_f32_e32 v111, v111
	v_exp_f32_e32 v106, v106
	v_add_f32_e32 v108, 1.0, v108
	v_add_f32_e32 v109, 1.0, v109
	v_rcp_f32_e32 v108, v108
	v_rcp_f32_e32 v109, v109
	v_rcp_f32_e32 v107, v104
	v_add_f32_e32 v104, 1.0, v105
	v_add_f32_e32 v110, 1.0, v110
	v_add_f32_e32 v111, 1.0, v111
	v_rcp_f32_e32 v117, v104
	v_add_f32_e32 v104, 1.0, v106
	v_mul_f32_e32 v96, 0xbfb8aa3b, v96
	v_rcp_f32_e32 v110, v110
	v_rcp_f32_e32 v111, v111
	v_rcp_f32_e32 v118, v104
	v_exp_f32_e32 v96, v96
	v_mul_f32_e32 v97, 0xbfb8aa3b, v97
	v_exp_f32_e32 v97, v97
	v_cvt_pk_bf16_f32 v104, v108, v109
	v_mov_b32_e32 v108, v148
	v_cvt_pk_bf16_f32 v105, v110, v111
	v_ashrrev_i32_e32 v109, 31, v108
	v_cvt_pk_bf16_f32 v106, v116, v107
	v_cvt_pk_bf16_f32 v107, v117, v118
	v_lshl_add_u64 v[108:109], v[108:109], 4, s[4:5]
	v_mul_f32_e32 v100, 0xbfb8aa3b, v100
	v_mul_f32_e32 v101, 0xbfb8aa3b, v101
	v_add_f32_e32 v96, 1.0, v96
	v_exp_f32_e32 v100, v100
	v_exp_f32_e32 v101, v101
	global_store_dwordx4 v[108:109], v[104:107], off
	v_mul_f32_e32 v102, 0xbfb8aa3b, v102
	v_mul_f32_e32 v103, 0xbfb8aa3b, v103
	v_rcp_f32_e32 v104, v96
	v_add_f32_e32 v96, 1.0, v97
	v_mul_f32_e32 v97, 0xbfb8aa3b, v98
	v_exp_f32_e32 v97, v97
	v_mul_f32_e32 v98, 0xbfb8aa3b, v99
	v_exp_f32_e32 v102, v102
	v_exp_f32_e32 v103, v103
	v_exp_f32_e32 v98, v98
	v_add_f32_e32 v100, 1.0, v100
	v_add_f32_e32 v101, 1.0, v101
	v_rcp_f32_e32 v100, v100
	v_rcp_f32_e32 v101, v101
	v_rcp_f32_e32 v99, v96
	v_add_f32_e32 v96, 1.0, v97
	v_add_f32_e32 v102, 1.0, v102
	v_add_f32_e32 v103, 1.0, v103
	v_rcp_f32_e32 v105, v96
	v_add_f32_e32 v96, 1.0, v98
	v_mul_f32_e32 v88, 0xbfb8aa3b, v88
	v_rcp_f32_e32 v102, v102
	v_rcp_f32_e32 v103, v103
	v_rcp_f32_e32 v106, v96
	v_exp_f32_e32 v88, v88
	v_mul_f32_e32 v89, 0xbfb8aa3b, v89
	v_exp_f32_e32 v89, v89
	v_cvt_pk_bf16_f32 v96, v100, v101
	v_mov_b32_e32 v100, v149
	v_cvt_pk_bf16_f32 v97, v102, v103
	v_ashrrev_i32_e32 v101, 31, v100
	v_cvt_pk_bf16_f32 v98, v104, v99
	v_cvt_pk_bf16_f32 v99, v105, v106
	v_lshl_add_u64 v[100:101], v[100:101], 4, s[4:5]
	v_mul_f32_e32 v92, 0xbfb8aa3b, v92
	v_mul_f32_e32 v93, 0xbfb8aa3b, v93
	v_add_f32_e32 v88, 1.0, v88
	v_exp_f32_e32 v92, v92
	v_exp_f32_e32 v93, v93
	global_store_dwordx4 v[100:101], v[96:99], off
	v_mul_f32_e32 v94, 0xbfb8aa3b, v94
	v_mul_f32_e32 v95, 0xbfb8aa3b, v95
	v_rcp_f32_e32 v96, v88
	v_add_f32_e32 v88, 1.0, v89
	v_mul_f32_e32 v89, 0xbfb8aa3b, v90
	v_exp_f32_e32 v89, v89
	v_mul_f32_e32 v90, 0xbfb8aa3b, v91
	v_exp_f32_e32 v94, v94
	v_exp_f32_e32 v95, v95
	v_exp_f32_e32 v90, v90
	v_add_f32_e32 v92, 1.0, v92
	v_add_f32_e32 v93, 1.0, v93
	v_rcp_f32_e32 v92, v92
	v_rcp_f32_e32 v93, v93
	v_rcp_f32_e32 v91, v88
	v_add_f32_e32 v88, 1.0, v89
	v_add_f32_e32 v94, 1.0, v94
	v_add_f32_e32 v95, 1.0, v95
	v_rcp_f32_e32 v97, v88
	v_add_f32_e32 v88, 1.0, v90
	v_mul_f32_e32 v80, 0xbfb8aa3b, v80
	v_rcp_f32_e32 v94, v94
	v_rcp_f32_e32 v95, v95
	v_rcp_f32_e32 v98, v88
	v_exp_f32_e32 v80, v80
	v_mul_f32_e32 v81, 0xbfb8aa3b, v81
	v_exp_f32_e32 v81, v81
	v_cvt_pk_bf16_f32 v88, v92, v93
	v_mov_b32_e32 v92, v150
	v_cvt_pk_bf16_f32 v89, v94, v95
	v_ashrrev_i32_e32 v93, 31, v92
	v_cvt_pk_bf16_f32 v90, v96, v91
	v_cvt_pk_bf16_f32 v91, v97, v98
	v_lshl_add_u64 v[92:93], v[92:93], 4, s[4:5]
	v_mul_f32_e32 v84, 0xbfb8aa3b, v84
	v_mul_f32_e32 v85, 0xbfb8aa3b, v85
	v_add_f32_e32 v80, 1.0, v80
	v_exp_f32_e32 v84, v84
	v_exp_f32_e32 v85, v85
	global_store_dwordx4 v[92:93], v[88:91], off
	v_mul_f32_e32 v86, 0xbfb8aa3b, v86
	v_mul_f32_e32 v87, 0xbfb8aa3b, v87
	v_rcp_f32_e32 v88, v80
	v_add_f32_e32 v80, 1.0, v81
	v_mul_f32_e32 v81, 0xbfb8aa3b, v82
	v_exp_f32_e32 v81, v81
	v_mul_f32_e32 v82, 0xbfb8aa3b, v83
	v_exp_f32_e32 v86, v86
	v_exp_f32_e32 v87, v87
	v_exp_f32_e32 v82, v82
	v_add_f32_e32 v84, 1.0, v84
	v_add_f32_e32 v85, 1.0, v85
	v_rcp_f32_e32 v84, v84
	v_rcp_f32_e32 v85, v85
	v_rcp_f32_e32 v83, v80
	v_add_f32_e32 v80, 1.0, v81
	v_add_f32_e32 v86, 1.0, v86
	v_add_f32_e32 v87, 1.0, v87
	v_rcp_f32_e32 v89, v80
	v_add_f32_e32 v80, 1.0, v82
	v_mul_f32_e32 v72, 0xbfb8aa3b, v72
	v_rcp_f32_e32 v86, v86
	v_rcp_f32_e32 v87, v87
	v_rcp_f32_e32 v90, v80
	v_exp_f32_e32 v72, v72
	v_mul_f32_e32 v73, 0xbfb8aa3b, v73
	v_exp_f32_e32 v73, v73
	v_cvt_pk_bf16_f32 v80, v84, v85
	v_mov_b32_e32 v84, v151
	v_cvt_pk_bf16_f32 v81, v86, v87
	v_ashrrev_i32_e32 v85, 31, v84
	v_cvt_pk_bf16_f32 v82, v88, v83
	v_cvt_pk_bf16_f32 v83, v89, v90
	v_lshl_add_u64 v[84:85], v[84:85], 4, s[4:5]
	v_mul_f32_e32 v76, 0xbfb8aa3b, v76
; __device__ __forceinline__ int launder_i(int x) { asm volatile("" : "+v"(x)); return x; }
; __device__ __forceinline__ float sigmoidf_(float x) { return __builtin_amdgcn_rcpf(1.f + __expf(-x)); }
; __device__ void phaseM1(const Params& p, char* lds) {
;     ...
;             {
; #pragma unroll
;                 for (int mi = 0; mi < 8; mi++)
; #pragma unroll
;                     for (int nh = 0; nh < 2; nh++) {
;                         const f32x4 a0 = acc[mi][2 * nh], a1 = acc[mi][2 * nh + 1];
;                         SG[(size_t)launder_i(pbase + (mi * 2 + nh) * 512)] = (u32x4){pack2(sigmoidf_(a0[0]), sigmoidf_(a0[1])), pack2(sigmoidf_(a0[2]), sigmoidf_(a0[3])),
;                                                                           pack2(sigmoidf_(a1[0]), sigmoidf_(a1[1])), pack2(sigmoidf_(a1[2]), sigmoidf_(a1[3]))};
;                     }
	v_mul_f32_e32 v77, 0xbfb8aa3b, v77
	v_add_f32_e32 v72, 1.0, v72
	v_exp_f32_e32 v76, v76
	v_exp_f32_e32 v77, v77
	global_store_dwordx4 v[84:85], v[80:83], off
	v_mul_f32_e32 v78, 0xbfb8aa3b, v78
	v_mul_f32_e32 v79, 0xbfb8aa3b, v79
	v_rcp_f32_e32 v80, v72
	v_add_f32_e32 v72, 1.0, v73
	v_mul_f32_e32 v73, 0xbfb8aa3b, v74
	v_exp_f32_e32 v73, v73
	v_mul_f32_e32 v74, 0xbfb8aa3b, v75
	v_exp_f32_e32 v78, v78
	v_exp_f32_e32 v79, v79
	v_exp_f32_e32 v74, v74
	v_add_f32_e32 v76, 1.0, v76
	v_add_f32_e32 v77, 1.0, v77
	v_rcp_f32_e32 v76, v76
	v_rcp_f32_e32 v77, v77
	v_rcp_f32_e32 v75, v72
	v_add_f32_e32 v72, 1.0, v73
	v_add_f32_e32 v78, 1.0, v78
	v_add_f32_e32 v79, 1.0, v79
	v_rcp_f32_e32 v81, v72
	v_add_f32_e32 v72, 1.0, v74
	v_mul_f32_e32 v64, 0xbfb8aa3b, v64
	v_rcp_f32_e32 v78, v78
	v_rcp_f32_e32 v79, v79
	v_rcp_f32_e32 v82, v72
	v_exp_f32_e32 v64, v64
	v_mul_f32_e32 v65, 0xbfb8aa3b, v65
	v_exp_f32_e32 v65, v65
	v_cvt_pk_bf16_f32 v72, v76, v77
	v_mov_b32_e32 v76, v152
	v_cvt_pk_bf16_f32 v73, v78, v79
	v_ashrrev_i32_e32 v77, 31, v76
	v_cvt_pk_bf16_f32 v74, v80, v75
	v_cvt_pk_bf16_f32 v75, v81, v82
	v_lshl_add_u64 v[76:77], v[76:77], 4, s[4:5]
	v_mul_f32_e32 v68, 0xbfb8aa3b, v68
	v_mul_f32_e32 v69, 0xbfb8aa3b, v69
	v_add_f32_e32 v64, 1.0, v64
	v_exp_f32_e32 v68, v68
	v_exp_f32_e32 v69, v69
	global_store_dwordx4 v[76:77], v[72:75], off
	v_mul_f32_e32 v70, 0xbfb8aa3b, v70
	v_mul_f32_e32 v71, 0xbfb8aa3b, v71
	v_rcp_f32_e32 v72, v64
	v_add_f32_e32 v64, 1.0, v65
	v_mul_f32_e32 v65, 0xbfb8aa3b, v66
	v_exp_f32_e32 v65, v65
	v_mul_f32_e32 v66, 0xbfb8aa3b, v67
	v_exp_f32_e32 v70, v70
	v_exp_f32_e32 v71, v71
	v_exp_f32_e32 v66, v66
	v_add_f32_e32 v68, 1.0, v68
	v_add_f32_e32 v69, 1.0, v69
	v_rcp_f32_e32 v68, v68
	v_rcp_f32_e32 v69, v69
	v_rcp_f32_e32 v67, v64
	v_add_f32_e32 v64, 1.0, v65
	v_add_f32_e32 v70, 1.0, v70
	v_add_f32_e32 v71, 1.0, v71
	v_rcp_f32_e32 v73, v64
	v_add_f32_e32 v64, 1.0, v66
	v_mul_f32_e32 v56, 0xbfb8aa3b, v56
	v_rcp_f32_e32 v70, v70
	v_rcp_f32_e32 v71, v71
	v_rcp_f32_e32 v74, v64
	v_exp_f32_e32 v56, v56
	v_mul_f32_e32 v57, 0xbfb8aa3b, v57
	v_exp_f32_e32 v57, v57
	v_cvt_pk_bf16_f32 v64, v68, v69
	v_mov_b32_e32 v68, v153
	v_cvt_pk_bf16_f32 v65, v70, v71
	v_ashrrev_i32_e32 v69, 31, v68
	v_cvt_pk_bf16_f32 v66, v72, v67
	v_cvt_pk_bf16_f32 v67, v73, v74
	v_lshl_add_u64 v[68:69], v[68:69], 4, s[4:5]
	v_mul_f32_e32 v60, 0xbfb8aa3b, v60
	v_mul_f32_e32 v61, 0xbfb8aa3b, v61
	v_add_f32_e32 v56, 1.0, v56
	v_exp_f32_e32 v60, v60
	v_exp_f32_e32 v61, v61
	global_store_dwordx4 v[68:69], v[64:67], off
	v_mul_f32_e32 v62, 0xbfb8aa3b, v62
	v_mul_f32_e32 v63, 0xbfb8aa3b, v63
	v_rcp_f32_e32 v64, v56
	v_add_f32_e32 v56, 1.0, v57
	v_mul_f32_e32 v57, 0xbfb8aa3b, v58
	v_exp_f32_e32 v57, v57
	v_mul_f32_e32 v58, 0xbfb8aa3b, v59
	v_exp_f32_e32 v62, v62
	v_exp_f32_e32 v63, v63
	v_exp_f32_e32 v58, v58
	v_add_f32_e32 v60, 1.0, v60
	v_add_f32_e32 v61, 1.0, v61
	v_rcp_f32_e32 v60, v60
	v_rcp_f32_e32 v61, v61
	v_rcp_f32_e32 v59, v56
	v_add_f32_e32 v56, 1.0, v57
	v_add_f32_e32 v62, 1.0, v62
	v_add_f32_e32 v63, 1.0, v63
	v_rcp_f32_e32 v65, v56
	v_add_f32_e32 v56, 1.0, v58
	v_mul_f32_e32 v48, 0xbfb8aa3b, v48
	v_rcp_f32_e32 v62, v62
	v_rcp_f32_e32 v63, v63
	v_rcp_f32_e32 v66, v56
	v_exp_f32_e32 v48, v48
	v_mul_f32_e32 v49, 0xbfb8aa3b, v49
	v_exp_f32_e32 v49, v49
	v_cvt_pk_bf16_f32 v56, v60, v61
	v_mov_b32_e32 v60, v154
	v_cvt_pk_bf16_f32 v57, v62, v63
	v_ashrrev_i32_e32 v61, 31, v60
	v_cvt_pk_bf16_f32 v58, v64, v59
	v_cvt_pk_bf16_f32 v59, v65, v66
	v_lshl_add_u64 v[60:61], v[60:61], 4, s[4:5]
	v_mul_f32_e32 v52, 0xbfb8aa3b, v52
	v_mul_f32_e32 v53, 0xbfb8aa3b, v53
	v_add_f32_e32 v48, 1.0, v48
	v_exp_f32_e32 v52, v52
	v_exp_f32_e32 v53, v53
	global_store_dwordx4 v[60:61], v[56:59], off
	v_mul_f32_e32 v54, 0xbfb8aa3b, v54
	v_mul_f32_e32 v55, 0xbfb8aa3b, v55
	v_rcp_f32_e32 v56, v48
	v_add_f32_e32 v48, 1.0, v49
	v_mul_f32_e32 v49, 0xbfb8aa3b, v50
	v_exp_f32_e32 v49, v49
	v_mul_f32_e32 v50, 0xbfb8aa3b, v51
	v_exp_f32_e32 v54, v54
	v_exp_f32_e32 v55, v55
	v_exp_f32_e32 v50, v50
	v_add_f32_e32 v52, 1.0, v52
	v_add_f32_e32 v53, 1.0, v53
	v_rcp_f32_e32 v52, v52
	v_rcp_f32_e32 v53, v53
	v_rcp_f32_e32 v51, v48
	v_add_f32_e32 v48, 1.0, v49
	v_add_f32_e32 v54, 1.0, v54
	v_add_f32_e32 v55, 1.0, v55
	v_rcp_f32_e32 v57, v48
	v_add_f32_e32 v48, 1.0, v50
	v_mul_f32_e32 v40, 0xbfb8aa3b, v40
	v_rcp_f32_e32 v54, v54
	v_rcp_f32_e32 v55, v55
	v_rcp_f32_e32 v58, v48
	v_exp_f32_e32 v40, v40
	v_mul_f32_e32 v41, 0xbfb8aa3b, v41
	v_exp_f32_e32 v41, v41
	v_cvt_pk_bf16_f32 v48, v52, v53
	v_mov_b32_e32 v52, v155
	v_cvt_pk_bf16_f32 v49, v54, v55
	v_ashrrev_i32_e32 v53, 31, v52
	v_cvt_pk_bf16_f32 v50, v56, v51
	v_cvt_pk_bf16_f32 v51, v57, v58
	v_lshl_add_u64 v[52:53], v[52:53], 4, s[4:5]
	v_mul_f32_e32 v44, 0xbfb8aa3b, v44
	v_mul_f32_e32 v45, 0xbfb8aa3b, v45
	v_add_f32_e32 v40, 1.0, v40
	v_exp_f32_e32 v44, v44
	v_exp_f32_e32 v45, v45
	global_store_dwordx4 v[52:53], v[48:51], off
	v_mul_f32_e32 v46, 0xbfb8aa3b, v46
	v_mul_f32_e32 v47, 0xbfb8aa3b, v47
	v_rcp_f32_e32 v48, v40
	v_add_f32_e32 v40, 1.0, v41
	v_mul_f32_e32 v41, 0xbfb8aa3b, v42
	v_exp_f32_e32 v41, v41
	v_mul_f32_e32 v42, 0xbfb8aa3b, v43
	v_exp_f32_e32 v46, v46
	v_exp_f32_e32 v47, v47
	v_exp_f32_e32 v42, v42
	v_add_f32_e32 v44, 1.0, v44
	v_add_f32_e32 v45, 1.0, v45
	v_rcp_f32_e32 v44, v44
	v_rcp_f32_e32 v45, v45
	v_rcp_f32_e32 v43, v40
	v_add_f32_e32 v40, 1.0, v41
	v_add_f32_e32 v46, 1.0, v46
	v_add_f32_e32 v47, 1.0, v47
	v_rcp_f32_e32 v49, v40
	v_add_f32_e32 v40, 1.0, v42
	v_mul_f32_e32 v32, 0xbfb8aa3b, v32
	v_rcp_f32_e32 v46, v46
	v_rcp_f32_e32 v47, v47
	v_rcp_f32_e32 v50, v40
	v_exp_f32_e32 v32, v32
	v_mul_f32_e32 v33, 0xbfb8aa3b, v33
; __device__ __forceinline__ int launder_i(int x) { asm volatile("" : "+v"(x)); return x; }
; __device__ __forceinline__ float sigmoidf_(float x) { return __builtin_amdgcn_rcpf(1.f + __expf(-x)); }
; __device__ void phaseM1(const Params& p, char* lds) {
;     ...
;             {
; #pragma unroll
;                 for (int mi = 0; mi < 8; mi++)
; #pragma unroll
;                     for (int nh = 0; nh < 2; nh++) {
;                         const f32x4 a0 = acc[mi][2 * nh], a1 = acc[mi][2 * nh + 1];
;                         SG[(size_t)launder_i(pbase + (mi * 2 + nh) * 512)] = (u32x4){pack2(sigmoidf_(a0[0]), sigmoidf_(a0[1])), pack2(sigmoidf_(a0[2]), sigmoidf_(a0[3])),
;                                                                           pack2(sigmoidf_(a1[0]), sigmoidf_(a1[1])), pack2(sigmoidf_(a1[2]), sigmoidf_(a1[3]))};
;                     }
	v_exp_f32_e32 v33, v33
	v_cvt_pk_bf16_f32 v40, v44, v45
	v_mov_b32_e32 v44, v156
	v_cvt_pk_bf16_f32 v41, v46, v47
	v_ashrrev_i32_e32 v45, 31, v44
	v_cvt_pk_bf16_f32 v42, v48, v43
	v_cvt_pk_bf16_f32 v43, v49, v50
	v_lshl_add_u64 v[44:45], v[44:45], 4, s[4:5]
	v_mul_f32_e32 v36, 0xbfb8aa3b, v36
	v_mul_f32_e32 v37, 0xbfb8aa3b, v37
	v_add_f32_e32 v32, 1.0, v32
	v_exp_f32_e32 v36, v36
	v_exp_f32_e32 v37, v37
	global_store_dwordx4 v[44:45], v[40:43], off
	v_mul_f32_e32 v38, 0xbfb8aa3b, v38
	v_mul_f32_e32 v39, 0xbfb8aa3b, v39
	v_rcp_f32_e32 v40, v32
	v_add_f32_e32 v32, 1.0, v33
	v_mul_f32_e32 v33, 0xbfb8aa3b, v34
	v_exp_f32_e32 v33, v33
	v_mul_f32_e32 v34, 0xbfb8aa3b, v35
	v_exp_f32_e32 v38, v38
	v_exp_f32_e32 v39, v39
	v_exp_f32_e32 v34, v34
	v_add_f32_e32 v36, 1.0, v36
	v_add_f32_e32 v37, 1.0, v37
	v_rcp_f32_e32 v36, v36
	v_rcp_f32_e32 v37, v37
	v_rcp_f32_e32 v35, v32
	v_add_f32_e32 v32, 1.0, v33
	v_add_f32_e32 v38, 1.0, v38
	v_add_f32_e32 v39, 1.0, v39
	v_rcp_f32_e32 v41, v32
	v_add_f32_e32 v32, 1.0, v34
	v_mul_f32_e32 v24, 0xbfb8aa3b, v24
	v_rcp_f32_e32 v38, v38
	v_rcp_f32_e32 v39, v39
	v_rcp_f32_e32 v42, v32
	v_exp_f32_e32 v24, v24
	v_mul_f32_e32 v25, 0xbfb8aa3b, v25
	v_exp_f32_e32 v25, v25
	v_cvt_pk_bf16_f32 v32, v36, v37
	v_mov_b32_e32 v36, v157
	v_cvt_pk_bf16_f32 v33, v38, v39
	v_ashrrev_i32_e32 v37, 31, v36
	v_cvt_pk_bf16_f32 v34, v40, v35
	v_cvt_pk_bf16_f32 v35, v41, v42
	v_lshl_add_u64 v[36:37], v[36:37], 4, s[4:5]
	v_mul_f32_e32 v28, 0xbfb8aa3b, v28
	v_mul_f32_e32 v29, 0xbfb8aa3b, v29
	v_add_f32_e32 v24, 1.0, v24
	v_exp_f32_e32 v28, v28
	v_exp_f32_e32 v29, v29
	global_store_dwordx4 v[36:37], v[32:35], off
	v_mul_f32_e32 v30, 0xbfb8aa3b, v30
	v_mul_f32_e32 v31, 0xbfb8aa3b, v31
	v_rcp_f32_e32 v32, v24
	v_add_f32_e32 v24, 1.0, v25
	v_mul_f32_e32 v25, 0xbfb8aa3b, v26
	v_exp_f32_e32 v25, v25
	v_mul_f32_e32 v26, 0xbfb8aa3b, v27
	v_exp_f32_e32 v30, v30
	v_exp_f32_e32 v31, v31
	v_exp_f32_e32 v26, v26
	v_add_f32_e32 v28, 1.0, v28
	v_add_f32_e32 v29, 1.0, v29
	v_rcp_f32_e32 v28, v28
	v_rcp_f32_e32 v29, v29
	v_rcp_f32_e32 v27, v24
	v_add_f32_e32 v24, 1.0, v25
	v_add_f32_e32 v30, 1.0, v30
	v_add_f32_e32 v31, 1.0, v31
	v_rcp_f32_e32 v33, v24
	v_add_f32_e32 v24, 1.0, v26
	v_mul_f32_e32 v16, 0xbfb8aa3b, v16
	v_rcp_f32_e32 v30, v30
	v_rcp_f32_e32 v31, v31
	v_rcp_f32_e32 v34, v24
	v_exp_f32_e32 v16, v16
	v_mul_f32_e32 v17, 0xbfb8aa3b, v17
	v_exp_f32_e32 v17, v17
	v_cvt_pk_bf16_f32 v24, v28, v29
	v_mov_b32_e32 v28, v160
	v_cvt_pk_bf16_f32 v25, v30, v31
	v_ashrrev_i32_e32 v29, 31, v28
	v_cvt_pk_bf16_f32 v26, v32, v27
	v_cvt_pk_bf16_f32 v27, v33, v34
	v_lshl_add_u64 v[28:29], v[28:29], 4, s[4:5]
	v_mul_f32_e32 v20, 0xbfb8aa3b, v20
	v_mul_f32_e32 v21, 0xbfb8aa3b, v21
	v_add_f32_e32 v16, 1.0, v16
	v_exp_f32_e32 v20, v20
	v_exp_f32_e32 v21, v21
	global_store_dwordx4 v[28:29], v[24:27], off
	v_mul_f32_e32 v22, 0xbfb8aa3b, v22
	v_mul_f32_e32 v23, 0xbfb8aa3b, v23
	v_rcp_f32_e32 v24, v16
	v_add_f32_e32 v16, 1.0, v17
	v_mul_f32_e32 v17, 0xbfb8aa3b, v18
	v_exp_f32_e32 v17, v17
	v_mul_f32_e32 v18, 0xbfb8aa3b, v19
	v_exp_f32_e32 v22, v22
	v_exp_f32_e32 v23, v23
	v_exp_f32_e32 v18, v18
	v_add_f32_e32 v20, 1.0, v20
	v_add_f32_e32 v21, 1.0, v21
	v_rcp_f32_e32 v20, v20
	v_rcp_f32_e32 v21, v21
	v_rcp_f32_e32 v19, v16
	v_add_f32_e32 v16, 1.0, v17
	v_add_f32_e32 v22, 1.0, v22
	v_add_f32_e32 v23, 1.0, v23
	v_rcp_f32_e32 v25, v16
	v_add_f32_e32 v16, 1.0, v18
	v_mul_f32_e32 v8, 0xbfb8aa3b, v8
	v_rcp_f32_e32 v22, v22
	v_rcp_f32_e32 v23, v23
	v_rcp_f32_e32 v26, v16
	v_exp_f32_e32 v8, v8
	v_mul_f32_e32 v9, 0xbfb8aa3b, v9
	v_exp_f32_e32 v9, v9
	v_cvt_pk_bf16_f32 v16, v20, v21
	v_mov_b32_e32 v20, v161
	v_cvt_pk_bf16_f32 v17, v22, v23
	v_ashrrev_i32_e32 v21, 31, v20
	v_cvt_pk_bf16_f32 v18, v24, v19
	v_cvt_pk_bf16_f32 v19, v25, v26
	v_lshl_add_u64 v[20:21], v[20:21], 4, s[4:5]
	v_mul_f32_e32 v12, 0xbfb8aa3b, v12
	v_mul_f32_e32 v13, 0xbfb8aa3b, v13
	v_add_f32_e32 v8, 1.0, v8
	v_exp_f32_e32 v12, v12
	v_exp_f32_e32 v13, v13
	global_store_dwordx4 v[20:21], v[16:19], off
	v_mul_f32_e32 v14, 0xbfb8aa3b, v14
	v_mul_f32_e32 v15, 0xbfb8aa3b, v15
	v_rcp_f32_e32 v16, v8
	v_add_f32_e32 v8, 1.0, v9
	v_mul_f32_e32 v9, 0xbfb8aa3b, v10
	v_exp_f32_e32 v9, v9
	v_mul_f32_e32 v10, 0xbfb8aa3b, v11
	v_exp_f32_e32 v14, v14
	v_exp_f32_e32 v15, v15
	v_exp_f32_e32 v10, v10
	v_add_f32_e32 v12, 1.0, v12
	v_add_f32_e32 v13, 1.0, v13
	v_rcp_f32_e32 v12, v12
	v_rcp_f32_e32 v13, v13
	v_rcp_f32_e32 v11, v8
	v_add_f32_e32 v8, 1.0, v9
	v_add_f32_e32 v14, 1.0, v14
	v_add_f32_e32 v15, 1.0, v15
	v_rcp_f32_e32 v17, v8
	v_add_f32_e32 v8, 1.0, v10
	v_mul_f32_e32 v0, 0xbfb8aa3b, v0
	v_rcp_f32_e32 v14, v14
	v_rcp_f32_e32 v15, v15
	v_rcp_f32_e32 v18, v8
	v_exp_f32_e32 v0, v0
	v_mul_f32_e32 v1, 0xbfb8aa3b, v1
	v_exp_f32_e32 v1, v1
	v_cvt_pk_bf16_f32 v8, v12, v13
	v_mov_b32_e32 v12, v162
	v_cvt_pk_bf16_f32 v9, v14, v15
	v_ashrrev_i32_e32 v13, 31, v12
	v_cvt_pk_bf16_f32 v10, v16, v11
	v_cvt_pk_bf16_f32 v11, v17, v18
	v_lshl_add_u64 v[12:13], v[12:13], 4, s[4:5]
	v_mul_f32_e32 v4, 0xbfb8aa3b, v4
	v_mul_f32_e32 v5, 0xbfb8aa3b, v5
; __device__ __forceinline__ int launder_i(int x) { asm volatile("" : "+v"(x)); return x; }
; #define TIDX512 launder_i((int)threadIdx.x)
; __device__ __forceinline__ float sigmoidf_(float x) { return __builtin_amdgcn_rcpf(1.f + __expf(-x)); }
; __device__ __forceinline__ void gemm_mainloop(f32x4 (&acc)[8][4], const GemmSrc& g, int K, char* lds) {
;     const int tid = TIDX512, lane = tid & 63, wave = tid >> 6;
;     const int wr = wave >> 2, wc = wave & 3, r = lane & 15, q = lane >> 4;
;     const int KT = K / 64;
;     const int rdo0 = r * 128 + ((q ^ (r >> 1)) * 16), rdo1 = r * 128 + (((4 + q) ^ (r >> 1)) * 16);
;     const int woff = 32768 + wc * 64 * 128, xoff = wr * 128 * 128;
; __device__ void phaseM1(const Params& p, char* lds) {
;     ...
;                 for (int mi = 0; mi < 8; mi++)
; #pragma unroll
;                     for (int nh = 0; nh < 2; nh++) {
;                         const f32x4 a0 = acc[mi][2 * nh], a1 = acc[mi][2 * nh + 1];
;                         SG[(size_t)launder_i(pbase + (mi * 2 + nh) * 512)] = (u32x4){pack2(sigmoidf_(a0[0]), sigmoidf_(a0[1])), pack2(sigmoidf_(a0[2]), sigmoidf_(a0[3])),
;                                                                           pack2(sigmoidf_(a1[0]), sigmoidf_(a1[1])), pack2(sigmoidf_(a1[2]), sigmoidf_(a1[3]))};
;                     }
;             }
;             zero_acc(acc);
;             gemm_mainloop(acc, g, DM, lds);
	v_add_f32_e32 v0, 1.0, v0
	v_exp_f32_e32 v4, v4
	v_exp_f32_e32 v5, v5
	global_store_dwordx4 v[12:13], v[8:11], off
	v_mul_f32_e32 v6, 0xbfb8aa3b, v6
	v_mul_f32_e32 v7, 0xbfb8aa3b, v7
	v_rcp_f32_e32 v8, v0
	v_add_f32_e32 v0, 1.0, v1
	v_mul_f32_e32 v1, 0xbfb8aa3b, v2
	v_exp_f32_e32 v1, v1
	v_mul_f32_e32 v2, 0xbfb8aa3b, v3
	v_exp_f32_e32 v6, v6
	v_exp_f32_e32 v7, v7
	v_exp_f32_e32 v2, v2
	v_add_f32_e32 v4, 1.0, v4
	v_add_f32_e32 v5, 1.0, v5
	v_rcp_f32_e32 v4, v4
	v_rcp_f32_e32 v5, v5
	v_rcp_f32_e32 v3, v0
	v_add_f32_e32 v0, 1.0, v1
	v_add_f32_e32 v6, 1.0, v6
	v_add_f32_e32 v7, 1.0, v7
	v_rcp_f32_e32 v9, v0
	v_add_f32_e32 v0, 1.0, v2
	v_rcp_f32_e32 v6, v6
	v_rcp_f32_e32 v7, v7
	v_rcp_f32_e32 v10, v0
	v_cvt_pk_bf16_f32 v0, v4, v5
	v_mov_b32_e32 v4, v163
	v_cvt_pk_bf16_f32 v1, v6, v7
	v_ashrrev_i32_e32 v5, 31, v4
	v_cvt_pk_bf16_f32 v2, v8, v3
	v_cvt_pk_bf16_f32 v3, v9, v10
	v_lshl_add_u64 v[4:5], v[4:5], 4, s[4:5]
	global_store_dwordx4 v[4:5], v[0:3], off
	s_mov_b32 s55, s31
	s_nop 0
	v_mov_b32_e32 v0, v158
	s_nop 0
	v_and_b32_e32 v1, 15, v0
	v_lshrrev_b32_e32 v2, 4, v0
	v_bfe_u32 v4, v0, 1, 3
	v_bfe_u32 v3, v0, 4, 2
	v_lshlrev_b32_e32 v1, 7, v1
	v_bitop3_b32 v2, v2, v4, 3 bitop3:0x6c
	v_lshl_or_b32 v164, v2, 4, v1
	v_bitop3_b32 v2, v3, v4, 4 bitop3:0x36
	v_lshl_or_b32 v135, v2, 4, v1
	v_lshlrev_b32_e32 v1, 7, v0
	v_lshlrev_b32_e32 v0, 6, v0
	v_and_b32_e32 v165, 0xffffc000, v0
	v_add3_u32 v0, s74, v115, v114
	v_add3_u32 v2, s48, v115, v114
	v_and_b32_e32 v166, 0x6000, v1
	v_mad_i64_i32 v[0:1], s[2:3], v0, s70, 0
	v_ashrrev_i32_e32 v3, 31, v2
	v_or_b32_e32 v0, v0, v128
	v_lshlrev_b64 v[2:3], 11, v[2:3]
	v_lshl_add_u64 v[0:1], v[0:1], 0, s[30:31]
	v_lshl_add_u64 v[2:3], s[54:55], 0, v[2:3]
	v_lshl_add_u64 v[136:137], s[6:7], 0, v[0:1]
	v_or_b32_e32 v2, v2, v128
	v_lshl_add_u64 v[0:1], v[0:1], 0, v[112:113]
	v_lshl_add_u64 v[140:141], s[6:7], 0, v[0:1]
	v_lshl_add_u64 v[0:1], v[2:3], 0, v[112:113]
	v_lshl_add_u64 v[142:143], s[6:7], 0, v[0:1]
	v_mov_b32_e32 v0, 0
	v_lshl_add_u64 v[138:139], s[6:7], 0, v[2:3]
	s_mov_b64 s[54:55], 0
	v_mov_b32_e32 v1, v0
	v_mov_b32_e32 v2, v0
	v_mov_b32_e32 v3, v0
	v_mov_b32_e32 v4, v0
	v_mov_b32_e32 v5, v0
	v_mov_b32_e32 v6, v0
	v_mov_b32_e32 v7, v0
	v_mov_b32_e32 v8, v0
	v_mov_b32_e32 v9, v0
	v_mov_b32_e32 v10, v0
	v_mov_b32_e32 v11, v0
	v_mov_b32_e32 v12, v0
	v_mov_b32_e32 v13, v0
	v_mov_b32_e32 v14, v0
	v_mov_b32_e32 v15, v0
	v_mov_b32_e32 v16, v0
	v_mov_b32_e32 v17, v0
	v_mov_b32_e32 v18, v0
	v_mov_b32_e32 v19, v0
	v_mov_b32_e32 v20, v0
	v_mov_b32_e32 v21, v0
	v_mov_b32_e32 v22, v0
	v_mov_b32_e32 v23, v0
	v_mov_b32_e32 v24, v0
	v_mov_b32_e32 v25, v0
	v_mov_b32_e32 v26, v0
	v_mov_b32_e32 v27, v0
	v_mov_b32_e32 v28, v0
	v_mov_b32_e32 v29, v0
	v_mov_b32_e32 v30, v0
	v_mov_b32_e32 v31, v0
	v_mov_b32_e32 v32, v0
	v_mov_b32_e32 v33, v0
	v_mov_b32_e32 v34, v0
	v_mov_b32_e32 v35, v0
	v_mov_b32_e32 v36, v0
	v_mov_b32_e32 v37, v0
	v_mov_b32_e32 v38, v0
	v_mov_b32_e32 v39, v0
	v_mov_b32_e32 v40, v0
	v_mov_b32_e32 v41, v0
	v_mov_b32_e32 v42, v0
	v_mov_b32_e32 v43, v0
	v_mov_b32_e32 v44, v0
	v_mov_b32_e32 v45, v0
	v_mov_b32_e32 v46, v0
	v_mov_b32_e32 v47, v0
	v_mov_b32_e32 v48, v0
	v_mov_b32_e32 v49, v0
	v_mov_b32_e32 v50, v0
	v_mov_b32_e32 v51, v0
	v_mov_b32_e32 v52, v0
	v_mov_b32_e32 v53, v0
	v_mov_b32_e32 v54, v0
	v_mov_b32_e32 v55, v0
	v_mov_b32_e32 v56, v0
	v_mov_b32_e32 v57, v0
	v_mov_b32_e32 v58, v0
	v_mov_b32_e32 v59, v0
	v_mov_b32_e32 v60, v0
	v_mov_b32_e32 v61, v0
	v_mov_b32_e32 v62, v0
	v_mov_b32_e32 v63, v0
	v_mov_b32_e32 v64, v0
	v_mov_b32_e32 v65, v0
	v_mov_b32_e32 v66, v0
	v_mov_b32_e32 v67, v0
	v_mov_b32_e32 v68, v0
	v_mov_b32_e32 v69, v0
	v_mov_b32_e32 v70, v0
	v_mov_b32_e32 v71, v0
	v_mov_b32_e32 v72, v0
	v_mov_b32_e32 v73, v0
	v_mov_b32_e32 v74, v0
	v_mov_b32_e32 v75, v0
	v_mov_b32_e32 v76, v0
	v_mov_b32_e32 v77, v0
	v_mov_b32_e32 v78, v0
	v_mov_b32_e32 v79, v0
	v_mov_b32_e32 v80, v0
	v_mov_b32_e32 v81, v0
	v_mov_b32_e32 v82, v0
	v_mov_b32_e32 v83, v0
	v_mov_b32_e32 v84, v0
	v_mov_b32_e32 v85, v0
	v_mov_b32_e32 v86, v0
	v_mov_b32_e32 v87, v0
	v_mov_b32_e32 v88, v0
	v_mov_b32_e32 v89, v0
	v_mov_b32_e32 v90, v0
	v_mov_b32_e32 v91, v0
	v_mov_b32_e32 v92, v0
	v_mov_b32_e32 v93, v0
	v_mov_b32_e32 v94, v0
	v_mov_b32_e32 v95, v0
	v_mov_b32_e32 v96, v0
	v_mov_b32_e32 v97, v0
	v_mov_b32_e32 v98, v0
	v_mov_b32_e32 v99, v0
	v_mov_b32_e32 v100, v0
	v_mov_b32_e32 v101, v0
	v_mov_b32_e32 v102, v0
	v_mov_b32_e32 v103, v0
	v_mov_b32_e32 v104, v0
	v_mov_b32_e32 v105, v0
	v_mov_b32_e32 v106, v0
	v_mov_b32_e32 v107, v0
	v_mov_b32_e32 v108, v0
	v_mov_b32_e32 v109, v0
	v_mov_b32_e32 v110, v0
	v_mov_b32_e32 v111, v0
	v_mov_b32_e32 v112, v0
	v_mov_b32_e32 v113, v0
	v_mov_b32_e32 v114, v0
	v_mov_b32_e32 v115, v0
	v_mov_b32_e32 v116, v0
	v_mov_b32_e32 v117, v0
	v_mov_b32_e32 v118, v0
	v_mov_b32_e32 v119, v0
	v_mov_b32_e32 v120, v0
	v_mov_b32_e32 v121, v0
	v_mov_b32_e32 v122, v0
	v_mov_b32_e32 v123, v0
	v_mov_b32_e32 v124, v0
	v_mov_b32_e32 v125, v0
	v_mov_b32_e32 v126, v0
	v_mov_b32_e32 v127, v0
	.p2alignl 6, 3212836864

; #define TIDX512 launder_i((int)threadIdx.x)
; __device__ __forceinline__ void glds16(const bf16_t* g, char* l) { __builtin_amdgcn_global_load_lds((const unsigned*)g, (unsigned*)l, 16, 0, 0); }
; __device__ __forceinline__ void gemm_issue(const GemmSrc& g, int kt, int s, char* lds) {
;     const int tid = TIDX512, lane = tid & 63, wave = tid >> 6;
;     char* xdst = lds + s * 65536 + wave * 4096 + lane * 16;
;     char* wdst = xdst + 32768;
; #pragma unroll
;     for (int i = 0; i < 4; i++) {
;         const int d = (i & 1) ? g.dsw : 0;
;         glds16(g.xsrc + (size_t)i * 8 * g.ldx + kt * 64 + d, xdst + i * 1024);
;         glds16(g.wsrc + (size_t)i * 8 * g.ldw + kt * 64 + d, wdst + i * 1024);
;     }
; }
; __device__ __forceinline__ void gemm_prologue(const GemmSrc& g, char* lds) { gemm_issue(g, 0, 0, lds); }
; __device__ void phaseM2(const Params& p, char* lds) {
;     ...
;         const int m0 = bm * 256, n0 = bn * 256;
;         f32x4 acc[8][4];
;         zero_acc(acc);
;         gemm_core(acc, M, DM, (const bf16_t*)(p.ws + OFF_WO), DM, DM, m0, n0, lds);
.LBB0_786:
	v_mov_b32_e32 v0, v158
	s_lshl_b32 s47, s47, 8
	v_ashrrev_i32_e32 v1, 1, v0
	v_and_b32_e32 v12, 0xffffffe0, v1
	v_bfe_u32 v1, v0, 4, 2
	v_and_b32_e32 v3, 7, v0
	v_bitop3_b32 v4, v1, v0, 7 bitop3:0x78
	v_bitop3_b32 v5, v1, v3, 4 bitop3:0x36
	v_lshlrev_b32_e32 v152, 4, v4
	v_sub_u32_e32 v4, v5, v4
	v_mov_b32_e32 v5, v158
	v_bfe_u32 v13, v0, 3, 3
	v_or_b32_e32 v2, v12, v13
	v_lshlrev_b32_e32 v6, 6, v5
	v_lshlrev_b32_e32 v5, 4, v5
	s_lshl_b32 s38, s48, 8
	v_add_u32_e32 v0, s47, v2
	v_and_b32_e32 v5, 0x3f0, v5
	v_ashrrev_i32_e32 v1, 31, v0
	v_add_u32_e32 v2, s38, v2
	v_and_or_b32 v14, v6, s42, v5
	v_lshlrev_b64 v[0:1], 11, v[0:1]
	v_ashrrev_i32_e32 v3, 31, v2
	v_lshlrev_b32_e32 v4, 3, v4
	v_add_u32_e32 v5, 0x8000, v14
	v_readfirstlane_b32 s39, v14
	v_lshl_add_u64 v[0:1], s[4:5], 0, v[0:1]
	v_lshlrev_b64 v[2:3], 11, v[2:3]
	s_mov_b32 m0, s39
	v_readfirstlane_b32 s39, v5
	v_ashrrev_i32_e32 v5, 31, v4
	v_lshl_add_u64 v[0:1], v[0:1], 0, v[152:153]
	v_lshl_add_u64 v[2:3], s[10:11], 0, v[2:3]
	v_lshlrev_b64 v[4:5], 1, v[4:5]
	v_or_b32_e32 v10, 0x400, v14
	v_lshl_add_u64 v[2:3], v[2:3], 0, v[152:153]
	global_load_lds_dwordx4 v[0:1], off
	s_mov_b32 m0, s39
	v_lshl_add_u64 v[6:7], v[0:1], 0, v[4:5]
	v_readfirstlane_b32 s39, v10
	global_load_lds_dwordx4 v[2:3], off
	v_lshl_add_u64 v[8:9], v[6:7], 0, s[12:13]
	s_mov_b32 m0, s39
	v_add_u32_e32 v15, 0x8400, v14
	global_load_lds_dwordx4 v[8:9], off
	v_lshl_add_u64 v[8:9], v[2:3], 0, v[4:5]
	v_readfirstlane_b32 s39, v15
	v_lshl_add_u64 v[10:11], v[8:9], 0, s[12:13]
	s_mov_b32 m0, s39
	v_lshl_add_u64 v[0:1], v[0:1], 0, s[14:15]
	global_load_lds_dwordx4 v[10:11], off
	v_or_b32_e32 v10, 0x800, v14
	s_mov_b64 s[40:41], 0
	v_readfirstlane_b32 s39, v10
	s_mov_b32 m0, s39
	s_nop 0
	global_load_lds_dwordx4 v[0:1], off
	v_lshl_add_u64 v[0:1], v[2:3], 0, s[14:15]
	v_add_u32_e32 v2, 0x8800, v14
	s_nop 0
	v_readfirstlane_b32 s39, v2
	v_or_b32_e32 v2, 0xc00, v14
	s_mov_b32 m0, s39
	v_readfirstlane_b32 s39, v2
	v_add_u32_e32 v2, 0x8c00, v14
	global_load_lds_dwordx4 v[0:1], off
	v_lshl_add_u64 v[0:1], v[6:7], 0, s[16:17]
	s_mov_b32 m0, s39
	v_readfirstlane_b32 s39, v2
	global_load_lds_dwordx4 v[0:1], off
	v_lshl_add_u64 v[0:1], v[8:9], 0, s[16:17]
	s_mov_b32 m0, s39
	s_mov_b32 s39, 0x10000
	global_load_lds_dwordx4 v[0:1], off
	v_mov_b32_e32 v0, v158
	s_nop 0
	v_and_b32_e32 v1, 15, v0
	v_lshrrev_b32_e32 v2, 4, v0
	v_bfe_u32 v6, v0, 1, 3
	v_bfe_u32 v3, v0, 4, 2
	v_lshlrev_b32_e32 v1, 7, v1
	v_bitop3_b32 v2, v2, v6, 3 bitop3:0x6c
	v_lshl_or_b32 v137, v2, 4, v1
	v_bitop3_b32 v2, v3, v6, 4 bitop3:0x36
	v_lshl_or_b32 v136, v2, 4, v1
	v_lshlrev_b32_e32 v1, 7, v0
	v_lshlrev_b32_e32 v0, 6, v0
	v_and_b32_e32 v138, 0xffffc000, v0
	v_or_b32_e32 v0, s47, v13
	v_add_u32_e32 v0, v0, v12
	v_or_b32_e32 v2, s38, v13
	v_and_b32_e32 v139, 0x6000, v1
	v_ashrrev_i32_e32 v1, 31, v0
	v_add_u32_e32 v2, v2, v12
	v_lshlrev_b64 v[0:1], 11, v[0:1]
	v_ashrrev_i32_e32 v3, 31, v2
	v_or_b32_e32 v0, v0, v152
	v_lshlrev_b64 v[2:3], 11, v[2:3]
	v_lshl_add_u64 v[128:129], s[6:7], 0, v[0:1]
	v_or_b32_e32 v2, v2, v152
	v_lshl_add_u64 v[0:1], v[0:1], 0, v[4:5]
	v_lshl_add_u64 v[132:133], s[6:7], 0, v[0:1]
	v_lshl_add_u64 v[0:1], v[2:3], 0, v[4:5]
	v_lshl_add_u64 v[134:135], s[6:7], 0, v[0:1]
	v_mov_b32_e32 v0, 0
	v_lshl_add_u64 v[130:131], s[6:7], 0, v[2:3]
	v_mov_b32_e32 v1, v0
	v_mov_b32_e32 v2, v0
	v_mov_b32_e32 v3, v0
	v_mov_b32_e32 v4, v0
	v_mov_b32_e32 v5, v0
	v_mov_b32_e32 v6, v0
	v_mov_b32_e32 v7, v0
	v_mov_b32_e32 v8, v0
	v_mov_b32_e32 v9, v0
	v_mov_b32_e32 v10, v0
	v_mov_b32_e32 v11, v0
	v_mov_b32_e32 v12, v0
	v_mov_b32_e32 v13, v0
	v_mov_b32_e32 v14, v0
	v_mov_b32_e32 v15, v0
	v_mov_b32_e32 v16, v0
	v_mov_b32_e32 v17, v0
	v_mov_b32_e32 v18, v0
	v_mov_b32_e32 v19, v0
	v_mov_b32_e32 v20, v0
	v_mov_b32_e32 v21, v0
	v_mov_b32_e32 v22, v0
	v_mov_b32_e32 v23, v0
	v_mov_b32_e32 v24, v0
	v_mov_b32_e32 v25, v0
	v_mov_b32_e32 v26, v0
	v_mov_b32_e32 v27, v0
	v_mov_b32_e32 v28, v0
	v_mov_b32_e32 v29, v0
	v_mov_b32_e32 v30, v0
	v_mov_b32_e32 v31, v0
	v_mov_b32_e32 v32, v0
	v_mov_b32_e32 v33, v0
	v_mov_b32_e32 v34, v0
	v_mov_b32_e32 v35, v0
	v_mov_b32_e32 v36, v0
	v_mov_b32_e32 v37, v0
	v_mov_b32_e32 v38, v0
	v_mov_b32_e32 v39, v0
	v_mov_b32_e32 v40, v0
	v_mov_b32_e32 v41, v0
	v_mov_b32_e32 v42, v0
	v_mov_b32_e32 v43, v0
	v_mov_b32_e32 v44, v0
	v_mov_b32_e32 v45, v0
	v_mov_b32_e32 v46, v0
	v_mov_b32_e32 v47, v0
	v_mov_b32_e32 v48, v0
	v_mov_b32_e32 v49, v0
	v_mov_b32_e32 v50, v0
	v_mov_b32_e32 v51, v0
	v_mov_b32_e32 v52, v0
	v_mov_b32_e32 v53, v0
	v_mov_b32_e32 v54, v0
	v_mov_b32_e32 v55, v0
	v_mov_b32_e32 v56, v0
	v_mov_b32_e32 v57, v0
	v_mov_b32_e32 v58, v0
	v_mov_b32_e32 v59, v0
	v_mov_b32_e32 v60, v0
	v_mov_b32_e32 v61, v0
	v_mov_b32_e32 v62, v0
	v_mov_b32_e32 v63, v0
	v_mov_b32_e32 v64, v0
	v_mov_b32_e32 v65, v0
	v_mov_b32_e32 v66, v0
	v_mov_b32_e32 v67, v0
	v_mov_b32_e32 v68, v0
	v_mov_b32_e32 v69, v0
	v_mov_b32_e32 v70, v0
	v_mov_b32_e32 v71, v0
	v_mov_b32_e32 v72, v0
	v_mov_b32_e32 v73, v0
	v_mov_b32_e32 v74, v0
	v_mov_b32_e32 v75, v0
	v_mov_b32_e32 v76, v0
	v_mov_b32_e32 v77, v0
	v_mov_b32_e32 v78, v0
	v_mov_b32_e32 v79, v0
	v_mov_b32_e32 v80, v0
	v_mov_b32_e32 v81, v0
	v_mov_b32_e32 v82, v0
	v_mov_b32_e32 v83, v0
	v_mov_b32_e32 v84, v0
	v_mov_b32_e32 v85, v0
	v_mov_b32_e32 v86, v0
	v_mov_b32_e32 v87, v0
	v_mov_b32_e32 v88, v0
	v_mov_b32_e32 v89, v0
	v_mov_b32_e32 v90, v0
	v_mov_b32_e32 v91, v0
	v_mov_b32_e32 v92, v0
	v_mov_b32_e32 v93, v0
	v_mov_b32_e32 v94, v0
	v_mov_b32_e32 v95, v0
	v_mov_b32_e32 v96, v0
	v_mov_b32_e32 v97, v0
	v_mov_b32_e32 v98, v0
	v_mov_b32_e32 v99, v0
	v_mov_b32_e32 v100, v0
	v_mov_b32_e32 v101, v0
	v_mov_b32_e32 v102, v0
	v_mov_b32_e32 v103, v0
	v_mov_b32_e32 v104, v0
	v_mov_b32_e32 v105, v0
	v_mov_b32_e32 v106, v0
	v_mov_b32_e32 v107, v0
	v_mov_b32_e32 v108, v0
	v_mov_b32_e32 v109, v0
	v_mov_b32_e32 v110, v0
	v_mov_b32_e32 v111, v0
	v_mov_b32_e32 v112, v0
	v_mov_b32_e32 v113, v0
	v_mov_b32_e32 v114, v0
	v_mov_b32_e32 v115, v0
	v_mov_b32_e32 v116, v0
	v_mov_b32_e32 v117, v0
	v_mov_b32_e32 v118, v0
	v_mov_b32_e32 v119, v0
	v_mov_b32_e32 v120, v0
	v_mov_b32_e32 v121, v0
	v_mov_b32_e32 v122, v0
	v_mov_b32_e32 v123, v0
	v_mov_b32_e32 v124, v0
	v_mov_b32_e32 v125, v0
	v_mov_b32_e32 v126, v0
	v_mov_b32_e32 v127, v0
	.p2alignl 6, 3212836864

; #define TIDX512 launder_i((int)threadIdx.x)
; __device__ __forceinline__ void glds16(const bf16_t* g, char* l) { __builtin_amdgcn_global_load_lds((const unsigned*)g, (unsigned*)l, 16, 0, 0); }
; __device__ __forceinline__ void gemm_issue(const GemmSrc& g, int kt, int s, char* lds) {
;     const int tid = TIDX512, lane = tid & 63, wave = tid >> 6;
;     char* xdst = lds + s * 65536 + wave * 4096 + lane * 16;
;     char* wdst = xdst + 32768;
; #pragma unroll
;     for (int i = 0; i < 4; i++) {
;         const int d = (i & 1) ? g.dsw : 0;
;         glds16(g.xsrc + (size_t)i * 8 * g.ldx + kt * 64 + d, xdst + i * 1024);
;         glds16(g.wsrc + (size_t)i * 8 * g.ldw + kt * 64 + d, wdst + i * 1024);
;     }
; }
; __device__ __forceinline__ void gemm_prologue(const GemmSrc& g, char* lds) { gemm_issue(g, 0, 0, lds); }
; __device__ void phaseP1(const Params& p, char* lds) {
;     ...
;         const int m0 = bm * 256, n0 = bn * 256;
;         f32x4 acc[8][4];
;         zero_acc(acc);
;         gemm_core(acc, H, DM, (const bf16_t*)(p.ws + OFF_WQ), DM, DM, m0, n0, lds);
.LBB0_918:
	v_mov_b32_e32 v0, v158
	s_lshl_b32 s42, s42, 8
	v_ashrrev_i32_e32 v1, 1, v0
	v_and_b32_e32 v12, 0xffffffe0, v1
	v_bfe_u32 v1, v0, 4, 2
	v_and_b32_e32 v3, 7, v0
	v_bitop3_b32 v4, v1, v0, 7 bitop3:0x78
	v_bitop3_b32 v5, v1, v3, 4 bitop3:0x36
	v_lshlrev_b32_e32 v128, 4, v4
	v_sub_u32_e32 v4, v5, v4
	v_mov_b32_e32 v5, v158
	v_bfe_u32 v13, v0, 3, 3
	v_or_b32_e32 v2, v12, v13
	v_lshlrev_b32_e32 v6, 6, v5
	v_lshlrev_b32_e32 v5, 4, v5
	s_lshl_b32 s34, s43, 8
	v_add_u32_e32 v0, s42, v2
	v_and_b32_e32 v5, 0x3f0, v5
	v_ashrrev_i32_e32 v1, 31, v0
	v_add_u32_e32 v2, s34, v2
	v_and_or_b32 v14, v6, s38, v5
	v_lshlrev_b64 v[0:1], 11, v[0:1]
	v_ashrrev_i32_e32 v3, 31, v2
	v_lshlrev_b32_e32 v4, 3, v4
	v_add_u32_e32 v5, 0x8000, v14
	v_readfirstlane_b32 s35, v14
	v_lshl_add_u64 v[0:1], s[6:7], 0, v[0:1]
	v_lshlrev_b64 v[2:3], 11, v[2:3]
	s_mov_b32 m0, s35
	v_readfirstlane_b32 s35, v5
	v_ashrrev_i32_e32 v5, 31, v4
	v_lshl_add_u64 v[0:1], v[0:1], 0, v[128:129]
	v_lshl_add_u64 v[2:3], s[8:9], 0, v[2:3]
	v_lshlrev_b64 v[4:5], 1, v[4:5]
	v_or_b32_e32 v10, 0x400, v14
	v_lshl_add_u64 v[2:3], v[2:3], 0, v[128:129]
	global_load_lds_dwordx4 v[0:1], off
	s_mov_b32 m0, s35
	v_lshl_add_u64 v[6:7], v[0:1], 0, v[4:5]
	v_readfirstlane_b32 s35, v10
	global_load_lds_dwordx4 v[2:3], off
	v_lshl_add_u64 v[8:9], v[6:7], 0, s[10:11]
	s_mov_b32 m0, s35
	v_add_u32_e32 v15, 0x8400, v14
	global_load_lds_dwordx4 v[8:9], off
	v_lshl_add_u64 v[8:9], v[2:3], 0, v[4:5]
	v_readfirstlane_b32 s35, v15
	v_lshl_add_u64 v[10:11], v[8:9], 0, s[10:11]
	s_mov_b32 m0, s35
	v_lshl_add_u64 v[0:1], v[0:1], 0, s[12:13]
	global_load_lds_dwordx4 v[10:11], off
	v_or_b32_e32 v10, 0x800, v14
	s_mov_b64 s[36:37], 0
	v_readfirstlane_b32 s35, v10
	s_mov_b32 m0, s35
	s_nop 0
	global_load_lds_dwordx4 v[0:1], off
	v_lshl_add_u64 v[0:1], v[2:3], 0, s[12:13]
	v_add_u32_e32 v2, 0x8800, v14
	s_nop 0
	v_readfirstlane_b32 s35, v2
	v_or_b32_e32 v2, 0xc00, v14
	s_mov_b32 m0, s35
	v_readfirstlane_b32 s35, v2
	v_add_u32_e32 v2, 0x8c00, v14
	global_load_lds_dwordx4 v[0:1], off
	v_lshl_add_u64 v[0:1], v[6:7], 0, s[14:15]
	s_mov_b32 m0, s35
	v_readfirstlane_b32 s35, v2
	global_load_lds_dwordx4 v[0:1], off
	v_lshl_add_u64 v[0:1], v[8:9], 0, s[14:15]
	s_mov_b32 m0, s35
	s_mov_b32 s35, 0x10000
	global_load_lds_dwordx4 v[0:1], off
	v_mov_b32_e32 v0, v158
	s_nop 0
	v_and_b32_e32 v1, 15, v0
	v_lshrrev_b32_e32 v2, 4, v0
	v_bfe_u32 v6, v0, 1, 3
	v_bfe_u32 v3, v0, 4, 2
	v_lshlrev_b32_e32 v1, 7, v1
	v_bitop3_b32 v2, v2, v6, 3 bitop3:0x6c
	v_lshl_or_b32 v140, v2, 4, v1
	v_bitop3_b32 v2, v3, v6, 4 bitop3:0x36
	v_lshl_or_b32 v139, v2, 4, v1
	v_lshlrev_b32_e32 v1, 7, v0
	v_lshlrev_b32_e32 v0, 6, v0
	v_and_b32_e32 v141, 0xffffc000, v0
	v_or_b32_e32 v0, s42, v13
	v_add_u32_e32 v0, v0, v12
	v_or_b32_e32 v2, s34, v13
	v_and_b32_e32 v142, 0x6000, v1
	v_ashrrev_i32_e32 v1, 31, v0
	v_add_u32_e32 v2, v2, v12
	v_lshlrev_b64 v[0:1], 11, v[0:1]
	v_ashrrev_i32_e32 v3, 31, v2
	v_or_b32_e32 v0, v0, v128
	v_lshlrev_b64 v[2:3], 11, v[2:3]
	v_lshl_add_u64 v[130:131], s[4:5], 0, v[0:1]
	v_or_b32_e32 v2, v2, v128
	v_lshl_add_u64 v[0:1], v[0:1], 0, v[4:5]
	v_lshl_add_u64 v[134:135], s[4:5], 0, v[0:1]
	v_lshl_add_u64 v[0:1], v[2:3], 0, v[4:5]
	v_lshl_add_u64 v[136:137], s[4:5], 0, v[0:1]
	v_mov_b32_e32 v0, 0
	v_lshl_add_u64 v[132:133], s[4:5], 0, v[2:3]
	v_mov_b32_e32 v1, v0
	v_mov_b32_e32 v2, v0
	v_mov_b32_e32 v3, v0
	v_mov_b32_e32 v4, v0
	v_mov_b32_e32 v5, v0
	v_mov_b32_e32 v6, v0
	v_mov_b32_e32 v7, v0
	v_mov_b32_e32 v8, v0
	v_mov_b32_e32 v9, v0
	v_mov_b32_e32 v10, v0
	v_mov_b32_e32 v11, v0
	v_mov_b32_e32 v12, v0
	v_mov_b32_e32 v13, v0
	v_mov_b32_e32 v14, v0
	v_mov_b32_e32 v15, v0
	v_mov_b32_e32 v16, v0
	v_mov_b32_e32 v17, v0
	v_mov_b32_e32 v18, v0
	v_mov_b32_e32 v19, v0
	v_mov_b32_e32 v20, v0
	v_mov_b32_e32 v21, v0
	v_mov_b32_e32 v22, v0
	v_mov_b32_e32 v23, v0
	v_mov_b32_e32 v24, v0
	v_mov_b32_e32 v25, v0
	v_mov_b32_e32 v26, v0
	v_mov_b32_e32 v27, v0
	v_mov_b32_e32 v28, v0
	v_mov_b32_e32 v29, v0
	v_mov_b32_e32 v30, v0
	v_mov_b32_e32 v31, v0
	v_mov_b32_e32 v32, v0
	v_mov_b32_e32 v33, v0
	v_mov_b32_e32 v34, v0
	v_mov_b32_e32 v35, v0
	v_mov_b32_e32 v36, v0
	v_mov_b32_e32 v37, v0
	v_mov_b32_e32 v38, v0
	v_mov_b32_e32 v39, v0
	v_mov_b32_e32 v40, v0
	v_mov_b32_e32 v41, v0
	v_mov_b32_e32 v42, v0
	v_mov_b32_e32 v43, v0
	v_mov_b32_e32 v44, v0
	v_mov_b32_e32 v45, v0
	v_mov_b32_e32 v46, v0
	v_mov_b32_e32 v47, v0
	v_mov_b32_e32 v48, v0
	v_mov_b32_e32 v49, v0
	v_mov_b32_e32 v50, v0
	v_mov_b32_e32 v51, v0
	v_mov_b32_e32 v52, v0
	v_mov_b32_e32 v53, v0
	v_mov_b32_e32 v54, v0
	v_mov_b32_e32 v55, v0
	v_mov_b32_e32 v56, v0
	v_mov_b32_e32 v57, v0
	v_mov_b32_e32 v58, v0
	v_mov_b32_e32 v59, v0
	v_mov_b32_e32 v60, v0
	v_mov_b32_e32 v61, v0
	v_mov_b32_e32 v62, v0
	v_mov_b32_e32 v63, v0
	v_mov_b32_e32 v64, v0
	v_mov_b32_e32 v65, v0
	v_mov_b32_e32 v66, v0
	v_mov_b32_e32 v67, v0
	v_mov_b32_e32 v68, v0
	v_mov_b32_e32 v69, v0
	v_mov_b32_e32 v70, v0
	v_mov_b32_e32 v71, v0
	v_mov_b32_e32 v72, v0
	v_mov_b32_e32 v73, v0
	v_mov_b32_e32 v74, v0
	v_mov_b32_e32 v75, v0
	v_mov_b32_e32 v76, v0
	v_mov_b32_e32 v77, v0
	v_mov_b32_e32 v78, v0
	v_mov_b32_e32 v79, v0
	v_mov_b32_e32 v80, v0
	v_mov_b32_e32 v81, v0
	v_mov_b32_e32 v82, v0
	v_mov_b32_e32 v83, v0
	v_mov_b32_e32 v84, v0
	v_mov_b32_e32 v85, v0
	v_mov_b32_e32 v86, v0
	v_mov_b32_e32 v87, v0
	v_mov_b32_e32 v88, v0
	v_mov_b32_e32 v89, v0
	v_mov_b32_e32 v90, v0
	v_mov_b32_e32 v91, v0
	v_mov_b32_e32 v92, v0
	v_mov_b32_e32 v93, v0
	v_mov_b32_e32 v94, v0
	v_mov_b32_e32 v95, v0
	v_mov_b32_e32 v96, v0
	v_mov_b32_e32 v97, v0
	v_mov_b32_e32 v98, v0
	v_mov_b32_e32 v99, v0
	v_mov_b32_e32 v100, v0
	v_mov_b32_e32 v101, v0
	v_mov_b32_e32 v102, v0
	v_mov_b32_e32 v103, v0
	v_mov_b32_e32 v104, v0
	v_mov_b32_e32 v105, v0
	v_mov_b32_e32 v106, v0
	v_mov_b32_e32 v107, v0
	v_mov_b32_e32 v108, v0
	v_mov_b32_e32 v109, v0
	v_mov_b32_e32 v110, v0
	v_mov_b32_e32 v111, v0
	v_mov_b32_e32 v112, v0
	v_mov_b32_e32 v113, v0
	v_mov_b32_e32 v114, v0
	v_mov_b32_e32 v115, v0
	v_mov_b32_e32 v116, v0
	v_mov_b32_e32 v117, v0
	v_mov_b32_e32 v118, v0
	v_mov_b32_e32 v119, v0
	v_mov_b32_e32 v120, v0
	v_mov_b32_e32 v121, v0
	v_mov_b32_e32 v122, v0
	v_mov_b32_e32 v123, v0
	v_mov_b32_e32 v124, v0
	v_mov_b32_e32 v125, v0
	v_mov_b32_e32 v126, v0
	v_mov_b32_e32 v127, v0
	.p2alignl 6, 3212836864

; __device__ __forceinline__ float bf_lo(unsigned u) { return __uint_as_float(u << 16); }
; __device__ __forceinline__ float bf_hi(unsigned u) { return __uint_as_float(u & 0xffff0000u); }
; __device__ __forceinline__ void p3_token(const Params& p, int tok, int lane, unsigned* rec, float& sh, int& hs8) {
;     ...
;     {
;         const u32x4 a = *(const u32x4*)(H + (size_t)tok * DM + lane * 16), b = *(const u32x4*)(H + (size_t)tok * DM + lane * 16 + 8);
;         const unsigned hw[8] = {a.x, a.y, a.z, a.w, b.x, b.y, b.z, b.w};
;         float hv[16];
;         float mx = 0.f;
; #pragma unroll
;         for (int i = 0; i < 8; i++) { hv[2 * i] = bf_lo(hw[i]); hv[2 * i + 1] = bf_hi(hw[i]); mx = fmaxf(mx, fmaxf(fabsf(hv[2 * i]), fabsf(hv[2 * i + 1]))); }
;         mx = wave_max(mx);
;         const float inv = mx > 0.f ? 119.f / mx : 0.f;
;         sh = mx * (1.f / 119.f);
;         unsigned qh[4] = {0u, 0u, 0u, 0u};
; #pragma unroll
;         for (int e = 0; e < 16; e++) {
;             const int qi = (int)rintf(hv[e] * inv);
;             const int hh = (qi + 8) >> 4, hl = qi - 16 * hh;
;             qh[(e >> 3) * 2] |= (unsigned)(hh & 15) << ((e & 7) * 4);
;             qh[(e >> 3) * 2 + 1] |= (unsigned)(hl & 15) << ((e & 7) * 4);
;         }
;         hs8 = 0;
;         *(u32x4*)(rec + 256 + lane * 4) = (u32x4){qh[0], qh[1], qh[2], qh[3]};
;     }
;     const int e0 = eidx[(size_t)tok * 128 + lane], e1 = eidx[(size_t)tok * 128 + 64 + lane];
;     const float g0 = gwp[(size_t)tok * 128 + lane], g1 = gwp[(size_t)tok * 128 + 64 + lane];
.LBB0_1042:
	v_ashrrev_i32_e32 v9, 31, v8
	s_waitcnt vmcnt(0)
	v_lshlrev_b64 v[28:29], 11, v[8:9]
	v_lshl_add_u64 v[30:31], v[20:21], 0, v[28:29]
	global_load_dwordx4 v[0:3], v[30:31], off
	global_load_dwordx4 v[4:7], v[30:31], off offset:16
	s_waitcnt vmcnt(1)
	v_lshlrev_b32_e32 v12, 16, v0
	v_and_b32_e32 v27, 0xffff0000, v0
	v_lshlrev_b32_e32 v36, 16, v1
	v_and_b32_e32 v37, 0xffff0000, v1
	v_lshlrev_b32_e32 v38, 16, v2
	v_and_b32_e32 v39, 0xffff0000, v2
	v_lshlrev_b32_e32 v40, 16, v3
	v_and_b32_e32 v41, 0xffff0000, v3
	v_max_f32_e64 v0, |v27|, |v27|
	v_max_f32_e64 v1, |v12|, |v12|
	v_max_f32_e64 v2, |v37|, |v37|
	v_max_f32_e64 v3, |v36|, |v36|
	s_waitcnt vmcnt(0)
	v_lshlrev_b32_e32 v42, 16, v4
	v_and_b32_e32 v43, 0xffff0000, v4
	v_lshlrev_b32_e32 v44, 16, v5
	v_and_b32_e32 v5, 0xffff0000, v5
	v_lshlrev_b32_e32 v45, 16, v6
	v_and_b32_e32 v46, 0xffff0000, v6
	v_lshlrev_b32_e32 v47, 16, v7
	v_and_b32_e32 v48, 0xffff0000, v7
	v_max_f32_e64 v4, |v39|, |v39|
	v_max_f32_e64 v6, |v38|, |v38|
	v_max_f32_e64 v7, |v41|, |v41|
	v_max_f32_e64 v30, |v40|, |v40|
	v_max_f32_e32 v0, v1, v0
	v_max_f32_e32 v1, v3, v2
	v_max_f32_e64 v31, |v43|, |v43|
	v_max_f32_e64 v32, |v42|, |v42|
	v_max_f32_e64 v33, |v5|, |v5|
	v_max_f32_e64 v34, |v44|, |v44|
	v_max_f32_e32 v2, v6, v4
	v_max_f32_e32 v3, v30, v7
	v_max3_f32 v0, v0, 0, v1
	v_max_f32_e64 v35, |v46|, |v46|
	v_max_f32_e64 v49, |v45|, |v45|
	v_max_f32_e64 v50, |v48|, |v48|
	v_max_f32_e64 v51, |v47|, |v47|
	v_max_f32_e32 v4, v32, v31
	v_max_f32_e32 v6, v34, v33
	v_max3_f32 v0, v0, v2, v3
	v_max_f32_e32 v7, v49, v35
	v_max_f32_e32 v30, v51, v50
	v_max3_f32 v0, v0, v4, v6
	v_max3_f32 v0, v0, v7, v30
	ds_bpermute_b32 v1, v112, v0
	s_waitcnt lgkmcnt(0)
	v_max_f32_e32 v1, v1, v1
	v_max_f32_e32 v0, v0, v1
	ds_bpermute_b32 v1, v113, v0
	s_waitcnt lgkmcnt(0)
	v_max_f32_e32 v1, v1, v1
	v_max_f32_e32 v0, v0, v1
	ds_bpermute_b32 v1, v114, v0
	s_waitcnt lgkmcnt(0)
	v_max_f32_e32 v1, v1, v1
	v_max_f32_e32 v0, v0, v1
	ds_bpermute_b32 v1, v115, v0
	s_waitcnt lgkmcnt(0)
	v_max_f32_e32 v1, v1, v1
	v_max_f32_e32 v2, v0, v1
	ds_bpermute_b32 v4, v116, v2
	v_lshlrev_b64 v[0:1], 9, v[8:9]
	v_lshl_or_b32 v0, v10, 2, v0
	v_mov_b32_e32 v3, v1
	v_lshl_add_u64 v[6:7], s[20:21], 0, v[0:1]
	s_waitcnt lgkmcnt(0)
	v_max_f32_e32 v4, v4, v4
	v_max_f32_e32 v4, v2, v4
	ds_bpermute_b32 v49, v117, v4
	v_or_b32_e32 v2, 0x100, v0
	v_lshl_add_u64 v[30:31], s[24:25], 0, v[0:1]
	v_lshl_add_u64 v[32:33], s[20:21], 0, v[2:3]
	v_lshl_add_u64 v[34:35], s[24:25], 0, v[2:3]
	s_waitcnt lgkmcnt(0)
	v_max_f32_e32 v0, v49, v49
	v_max_f32_e32 v0, v4, v0
	global_load_dword v4, v[6:7], off
	global_load_dword v1, v[32:33], off
	global_load_dword v2, v[30:31], off
	global_load_dword v3, v[34:35], off
	v_div_scale_f32 v49, s[4:5], v0, v0, s33
	v_rcp_f32_e32 v50, v49
	v_div_scale_f32 v6, vcc, s33, v0, s33
	v_fma_f32 v7, -v49, v50, 1.0
	v_fmac_f32_e32 v50, v7, v50
	v_mul_f32_e32 v7, v6, v50
	v_fma_f32 v30, -v49, v7, v6
	v_fmac_f32_e32 v7, v30, v50
	v_fma_f32 v6, -v49, v7, v6
	v_div_fmas_f32 v6, v6, v50, v7
	v_div_fixup_f32 v6, v6, v0, s33
	v_cmp_lt_f32_e32 vcc, 0, v0
	s_waitcnt vmcnt(2)
	v_cmp_gt_u32_e64 s[4:5], s37, v1
	v_cndmask_b32_e32 v6, 0, v6, vcc
	v_mul_f32_e32 v7, v6, v12
	v_mul_f32_e32 v12, v6, v27
	v_mul_f32_e32 v27, v6, v36
	v_mul_f32_e32 v30, v6, v37
	v_rndne_f32_e32 v7, v7
	v_rndne_f32_e32 v12, v12
	v_mul_f32_e32 v31, v6, v38
	v_mul_f32_e32 v32, v6, v39
	v_mul_f32_e32 v34, v6, v41
	v_rndne_f32_e32 v27, v27
	v_rndne_f32_e32 v30, v30
	v_cvt_i32_f32_e32 v7, v7
	v_cvt_i32_f32_e32 v12, v12
	v_mul_f32_e32 v33, v6, v40
	v_rndne_f32_e32 v31, v31
	v_rndne_f32_e32 v32, v32
	v_rndne_f32_e32 v34, v34
	v_cvt_i32_f32_e32 v27, v27
	v_cvt_i32_f32_e32 v30, v30
	v_rndne_f32_e32 v33, v33
	v_cvt_i32_f32_e32 v31, v31
	v_cvt_i32_f32_e32 v32, v32
	v_cvt_i32_f32_e32 v34, v34
	v_cvt_i32_f32_e32 v33, v33
	v_add_u32_e32 v36, 8, v7
	v_add_u32_e32 v37, 8, v12
	v_and_b32_e32 v7, 15, v7
	v_lshlrev_b32_e32 v12, 4, v12
	v_lshl_add_u32 v38, v27, 4, v122
	v_lshlrev_b32_e32 v27, 8, v27
	v_lshl_add_u32 v39, v30, 8, v123
	v_lshrrev_b32_e32 v36, 4, v36
	v_and_b32_e32 v37, 0xf0, v37
	v_lshl_add_u32 v40, v31, 12, v124
	v_lshl_add_u32 v41, v32, 16, v125
	v_lshl_add_u32 v49, v34, 24, v127
	v_and_b32_e32 v12, 0xf0, v12
	v_and_b32_e32 v38, 0xf00, v38
	v_and_b32_e32 v27, 0xf00, v27
	v_and_b32_e32 v39, 0xf000, v39
	v_lshl_or_b32 v7, v34, 28, v7
	v_and_or_b32 v34, v36, 15, v37
	v_mul_f32_e32 v35, v6, v42
	v_lshlrev_b32_e32 v30, 12, v30
	v_lshlrev_b32_e32 v31, 16, v31
	v_lshl_add_u32 v42, v33, 20, v126
	v_and_b32_e32 v40, 0xf0000, v40
	v_and_b32_e32 v41, 0xf00000, v41
	v_or3_b32 v7, v7, v12, v27
	v_or3_b32 v12, v34, v38, v39
	v_and_b32_e32 v30, 0xf000, v30
	v_and_b32_e32 v31, 0xf0000, v31
	v_and_b32_e32 v42, 0xf000000, v42
	v_and_b32_e32 v49, 0xf0000000, v49
	v_or3_b32 v12, v12, v40, v41
	v_lshlrev_b32_e32 v32, 20, v32
	v_lshlrev_b32_e32 v33, 24, v33
	v_or3_b32 v7, v7, v30, v31
	v_or3_b32 v30, v12, v42, v49
	v_mul_f32_e32 v12, v6, v43
	v_rndne_f32_e32 v35, v35
	v_and_b32_e32 v32, 0xf00000, v32
	v_and_b32_e32 v33, 0xf000000, v33
	v_rndne_f32_e32 v12, v12
	v_or3_b32 v31, v7, v32, v33
	v_cvt_i32_f32_e32 v7, v35
	v_cvt_i32_f32_e32 v12, v12
	v_mul_f32_e32 v33, v6, v44
	v_mul_f32_e32 v5, v6, v5
	v_rndne_f32_e32 v33, v33
	v_rndne_f32_e32 v5, v5
	v_cvt_i32_f32_e32 v33, v33
	v_cvt_i32_f32_e32 v5, v5
	v_add_u32_e32 v27, 8, v7
	v_add_u32_e32 v32, 8, v12
	v_lshrrev_b32_e32 v27, 4, v27
	v_and_b32_e32 v32, 0xf0, v32
	v_and_or_b32 v27, v27, 15, v32
	v_lshl_add_u32 v32, v33, 4, v122
	v_lshl_add_u32 v34, v5, 8, v123
	v_and_b32_e32 v32, 0xf00, v32
	v_and_b32_e32 v34, 0xf000, v34
	v_mul_f32_e32 v35, v6, v45
; __device__ __forceinline__ float bf_lo(unsigned u) { return __uint_as_float(u << 16); }
; __device__ __forceinline__ float bf_hi(unsigned u) { return __uint_as_float(u & 0xffff0000u); }
; __device__ __forceinline__ void p3_token(const Params& p, int tok, int lane, unsigned* rec, float& sh, int& hs8) {
;     ...
;         const u32x4 a = *(const u32x4*)(H + (size_t)tok * DM + lane * 16), b = *(const u32x4*)(H + (size_t)tok * DM + lane * 16 + 8);
;         const unsigned hw[8] = {a.x, a.y, a.z, a.w, b.x, b.y, b.z, b.w};
;         float hv[16];
;         float mx = 0.f;
; #pragma unroll
;         for (int i = 0; i < 8; i++) { hv[2 * i] = bf_lo(hw[i]); hv[2 * i + 1] = bf_hi(hw[i]); mx = fmaxf(mx, fmaxf(fabsf(hv[2 * i]), fabsf(hv[2 * i + 1]))); }
;     ...
;     const int e0 = eidx[(size_t)tok * 128 + lane], e1 = eidx[(size_t)tok * 128 + 64 + lane];
;     const float g0 = gwp[(size_t)tok * 128 + lane], g1 = gwp[(size_t)tok * 128 + 64 + lane];
;     const int k0 = e0 >> 11, k1 = e1 >> 11;
;     int pos0 = 0, pos1 = 0, base = 0;
; #pragma unroll
;     for (int v = 0; v < 8; v++) {
;         const unsigned long long m0 = __ballot(k0 == v), m1 = __ballot(k1 == v);
;         const int c0 = __popcll(m0);
;         const int r0 = __builtin_amdgcn_mbcnt_hi((unsigned)(m0 >> 32), __builtin_amdgcn_mbcnt_lo((unsigned)m0, 0u));
;         const int r1 = __builtin_amdgcn_mbcnt_hi((unsigned)(m1 >> 32), __builtin_amdgcn_mbcnt_lo((unsigned)m1, 0u));
;         pos0 = (k0 == v) ? base + r0 : pos0;
;         pos1 = (k1 == v) ? base + c0 + r1 : pos1;
;         base += c0 + __popcll(m1);
;     }
	v_or3_b32 v27, v27, v32, v34
	v_mul_f32_e32 v34, v6, v46
	v_rndne_f32_e32 v35, v35
	v_rndne_f32_e32 v34, v34
	v_cvt_i32_f32_e32 v35, v35
	v_cvt_i32_f32_e32 v34, v34
	v_mul_f32_e32 v37, v6, v47
	v_mul_f32_e32 v6, v6, v48
	v_rndne_f32_e32 v37, v37
	v_rndne_f32_e32 v6, v6
	v_cvt_i32_f32_e32 v37, v37
	v_cvt_i32_f32_e32 v6, v6
	v_lshl_add_u32 v32, v35, 12, v124
	v_lshl_add_u32 v36, v34, 16, v125
	v_and_b32_e32 v32, 0xf0000, v32
	v_and_b32_e32 v36, 0xf00000, v36
	v_and_b32_e32 v7, 15, v7
	v_lshlrev_b32_e32 v12, 4, v12
	v_lshlrev_b32_e32 v33, 8, v33
	v_or3_b32 v27, v27, v32, v36
	v_lshlrev_b32_e32 v32, 20, v34
	v_and_b32_e32 v12, 0xf0, v12
	v_and_b32_e32 v33, 0xf00, v33
	v_lshlrev_b32_e32 v5, 12, v5
	v_lshlrev_b32_e32 v35, 16, v35
	v_and_b32_e32 v34, 0xf00000, v32
	v_lshl_add_u32 v32, v37, 20, v126
	v_lshlrev_b32_e32 v36, 24, v37
	v_lshl_add_u32 v37, v6, 24, v127
	v_lshl_or_b32 v6, v6, 28, v7
	v_and_b32_e32 v5, 0xf000, v5
	v_and_b32_e32 v35, 0xf0000, v35
	v_or3_b32 v6, v6, v12, v33
	v_and_b32_e32 v32, 0xf000000, v32
	v_and_b32_e32 v36, 0xf000000, v36
	v_and_b32_e32 v37, 0xf0000000, v37
	v_or3_b32 v5, v6, v5, v35
	v_cmp_gt_u32_e32 vcc, s37, v4
	v_or3_b32 v32, v27, v32, v37
	v_or3_b32 v33, v5, v34, v36
	s_bcnt1_i32_b64 s8, vcc
	v_mov_b32_e32 v5, v13
	ds_write_b128 v128, v[30:33] offset:1024
	s_and_saveexec_b64 s[6:7], s[4:5]
	v_mbcnt_lo_u32_b32 v5, s4, 0
	v_mbcnt_hi_u32_b32 v5, s5, v5
	v_add_u32_e32 v5, s8, v5
	s_or_b64 exec, exec, s[6:7]
	v_ashrrev_i32_e32 v6, 11, v4
	s_bcnt1_i32_b64 s42, s[4:5]
	v_cmp_eq_u32_e64 s[4:5], 1, v6
	v_ashrrev_i32_e32 v7, 11, v1
	s_add_i32 s42, s42, s8
	s_bcnt1_i32_b64 s8, s[4:5]
	v_cmp_eq_u32_e64 s[6:7], 1, v7
	s_add_i32 s43, s42, s8
	s_and_saveexec_b64 s[8:9], s[6:7]
	v_mbcnt_lo_u32_b32 v5, s6, 0
	v_mbcnt_hi_u32_b32 v5, s7, v5
	v_add_u32_e32 v5, s43, v5
	s_or_b64 exec, exec, s[8:9]
	s_bcnt1_i32_b64 s6, s[6:7]
	s_add_i32 s43, s43, s6
	v_cmp_eq_u32_e64 s[6:7], 2, v6
	s_bcnt1_i32_b64 s10, s[6:7]
	v_cmp_eq_u32_e64 s[8:9], 2, v7
	s_add_i32 s44, s43, s10
	s_and_saveexec_b64 s[10:11], s[8:9]
	v_mbcnt_lo_u32_b32 v5, s8, 0
	v_mbcnt_hi_u32_b32 v5, s9, v5
	v_add_u32_e32 v5, s44, v5
	s_or_b64 exec, exec, s[10:11]
	s_bcnt1_i32_b64 s8, s[8:9]
	s_add_i32 s44, s44, s8
	v_cmp_eq_u32_e64 s[8:9], 3, v6
	s_bcnt1_i32_b64 s12, s[8:9]
	v_cmp_eq_u32_e64 s[10:11], 3, v7
	s_add_i32 s45, s44, s12
	s_and_saveexec_b64 s[12:13], s[10:11]
	v_mbcnt_lo_u32_b32 v5, s10, 0
	v_mbcnt_hi_u32_b32 v5, s11, v5
	v_add_u32_e32 v5, s45, v5
	s_or_b64 exec, exec, s[12:13]
	s_bcnt1_i32_b64 s10, s[10:11]
	s_add_i32 s45, s45, s10
	v_cmp_eq_u32_e64 s[10:11], 4, v6
	s_bcnt1_i32_b64 s14, s[10:11]
	v_cmp_eq_u32_e64 s[12:13], 4, v7
	s_add_i32 s46, s45, s14
	s_and_saveexec_b64 s[14:15], s[12:13]
	v_mbcnt_lo_u32_b32 v5, s12, 0
	v_mbcnt_hi_u32_b32 v5, s13, v5
	v_add_u32_e32 v5, s46, v5
	s_or_b64 exec, exec, s[14:15]
	s_bcnt1_i32_b64 s12, s[12:13]
	s_add_i32 s46, s46, s12
	v_cmp_eq_u32_e64 s[12:13], 5, v6
	s_bcnt1_i32_b64 s16, s[12:13]
	v_cmp_eq_u32_e64 s[14:15], 5, v7
	s_add_i32 s47, s46, s16
	s_and_saveexec_b64 s[16:17], s[14:15]
	v_mbcnt_lo_u32_b32 v5, s14, 0
	v_mbcnt_hi_u32_b32 v5, s15, v5
	v_add_u32_e32 v5, s47, v5
	s_or_b64 exec, exec, s[16:17]
	s_bcnt1_i32_b64 s14, s[14:15]
	s_add_i32 s47, s47, s14
	v_cmp_eq_u32_e64 s[14:15], 6, v6
	s_bcnt1_i32_b64 s18, s[14:15]
	v_cmp_eq_u32_e64 s[16:17], 6, v7
	s_add_i32 s48, s47, s18
	s_and_saveexec_b64 s[18:19], s[16:17]
	v_mbcnt_lo_u32_b32 v5, s16, 0
	v_mbcnt_hi_u32_b32 v5, s17, v5
	v_add_u32_e32 v5, s48, v5
	s_or_b64 exec, exec, s[18:19]
	s_bcnt1_i32_b64 s16, s[16:17]
	s_add_i32 s48, s48, s16
	v_cmp_eq_u32_e64 s[16:17], 7, v6
	v_cmp_eq_u32_e64 s[18:19], 7, v7
	s_and_saveexec_b64 s[34:35], s[18:19]
	s_bcnt1_i32_b64 s49, s[16:17]
	v_mbcnt_lo_u32_b32 v5, s18, 0
	s_add_i32 s49, s48, s49
	v_mbcnt_hi_u32_b32 v5, s19, v5
	v_add_u32_e32 v5, s49, v5
	s_or_b64 exec, exec, s[34:35]
	v_or_b32_e32 v30, 1, v8
	v_ashrrev_i32_e32 v31, 31, v30
	v_lshlrev_b64 v[32:33], 11, v[30:31]
	v_lshl_add_u64 v[6:7], v[20:21], 0, v[32:33]
	global_load_dwordx4 v[34:37], v[6:7], off
	global_load_dwordx4 v[38:41], v[6:7], off offset:16
	v_mbcnt_lo_u32_b32 v7, s16, 0
	v_lshlrev_b32_e32 v6, 1, v4
	v_mbcnt_lo_u32_b32 v43, s12, 0
	v_lshlrev_b32_e32 v42, 1, v1
	v_mbcnt_hi_u32_b32 v51, s17, v7
	v_ashrrev_i32_e32 v7, 31, v6
	v_mbcnt_lo_u32_b32 v44, s10, 0
	v_mbcnt_lo_u32_b32 v45, s8, 0
	v_mbcnt_hi_u32_b32 v52, s13, v43
	v_ashrrev_i32_e32 v43, 31, v42
	v_lshl_add_u64 v[6:7], v[6:7], 2, s[26:27]
	v_mbcnt_hi_u32_b32 v53, s11, v44
	v_mbcnt_hi_u32_b32 v54, s9, v45
	v_lshl_add_u64 v[42:43], v[42:43], 2, s[26:27]
	global_load_dwordx2 v[44:45], v[6:7], off
	global_load_dwordx2 v[46:47], v[42:43], off
	v_mbcnt_lo_u32_b32 v48, s6, 0
	v_mbcnt_lo_u32_b32 v49, s4, 0
	v_mbcnt_lo_u32_b32 v50, vcc_lo, 0
	v_mbcnt_hi_u32_b32 v6, s7, v48
	v_mbcnt_hi_u32_b32 v7, s5, v49
	v_mbcnt_hi_u32_b32 v42, vcc_hi, v50
	v_add_u32_e32 v43, s48, v51
	v_add_u32_e32 v7, s42, v7
	v_cndmask_b32_e32 v42, 0, v42, vcc
	v_add_u32_e32 v6, s43, v6
	v_cndmask_b32_e64 v7, v42, v7, s[4:5]
	v_cndmask_b32_e64 v6, v7, v6, s[6:7]
	v_mbcnt_lo_u32_b32 v27, s14, 0
	v_mbcnt_hi_u32_b32 v27, s15, v27
	v_add_u32_e32 v27, s47, v27
	v_lshl_add_u32 v5, v5, 2, v11
	v_mul_f32_e32 v12, 0x3c09ae41, v0
	v_mov_b32_e32 v0, 0
	s_waitcnt vmcnt(3)
	v_lshlrev_b32_e32 v48, 16, v34
	v_and_b32_e32 v34, 0xffff0000, v34
	v_lshlrev_b32_e32 v49, 16, v35
	v_and_b32_e32 v35, 0xffff0000, v35
	v_lshlrev_b32_e32 v50, 16, v36
	v_and_b32_e32 v36, 0xffff0000, v36
	v_lshlrev_b32_e32 v51, 16, v37
	v_and_b32_e32 v55, 0xffff0000, v37
	s_waitcnt vmcnt(2)
; __device__ __forceinline__ float bf_lo(unsigned u) { return __uint_as_float(u << 16); }
; __device__ __forceinline__ float bf_hi(unsigned u) { return __uint_as_float(u & 0xffff0000u); }
; __device__ __forceinline__ void p3_token(const Params& p, int tok, int lane, unsigned* rec, float& sh, int& hs8) {
;     ...
;         for (int i = 0; i < 8; i++) { hv[2 * i] = bf_lo(hw[i]); hv[2 * i + 1] = bf_hi(hw[i]); mx = fmaxf(mx, fmaxf(fabsf(hv[2 * i]), fabsf(hv[2 * i + 1]))); }
;         mx = wave_max(mx);
;         const float inv = mx > 0.f ? 119.f / mx : 0.f;
;         sh = mx * (1.f / 119.f);
;         unsigned qh[4] = {0u, 0u, 0u, 0u};
; #pragma unroll
;         for (int e = 0; e < 16; e++) {
;             const int qi = (int)rintf(hv[e] * inv);
;             const int hh = (qi + 8) >> 4, hl = qi - 16 * hh;
;             qh[(e >> 3) * 2] |= (unsigned)(hh & 15) << ((e & 7) * 4);
;             qh[(e >> 3) * 2 + 1] |= (unsigned)(hl & 15) << ((e & 7) * 4);
;         }
;         hs8 = 0;
;         *(u32x4*)(rec + 256 + lane * 4) = (u32x4){qh[0], qh[1], qh[2], qh[3]};
;     ...
;     const int e0 = eidx[(size_t)tok * 128 + lane], e1 = eidx[(size_t)tok * 128 + 64 + lane];
;     const float g0 = gwp[(size_t)tok * 128 + lane], g1 = gwp[(size_t)tok * 128 + 64 + lane];
;     const int k0 = e0 >> 11, k1 = e1 >> 11;
	v_lshlrev_b32_e32 v56, 16, v38
	v_and_b32_e32 v57, 0xffff0000, v38
	v_lshlrev_b32_e32 v58, 16, v39
	v_and_b32_e32 v59, 0xffff0000, v39
	v_max_f32_e64 v37, |v34|, |v34|
	v_max_f32_e64 v38, |v48|, |v48|
	v_max_f32_e64 v39, |v35|, |v35|
	v_max_f32_e64 v62, |v49|, |v49|
	v_max_f32_e64 v63, |v36|, |v36|
	v_max_f32_e64 v64, |v50|, |v50|
	v_max_f32_e64 v65, |v55|, |v55|
	v_max_f32_e64 v66, |v51|, |v51|
	v_max_f32_e32 v37, v38, v37
	v_max_f32_e32 v38, v62, v39
	v_lshlrev_b32_e32 v60, 16, v40
	v_and_b32_e32 v40, 0xffff0000, v40
	v_lshlrev_b32_e32 v61, 16, v41
	v_and_b32_e32 v41, 0xffff0000, v41
	v_max_f32_e64 v67, |v57|, |v57|
	v_max_f32_e64 v68, |v56|, |v56|
	v_max_f32_e64 v69, |v59|, |v59|
	v_max_f32_e64 v70, |v58|, |v58|
	v_max_f32_e32 v39, v64, v63
	v_max_f32_e32 v62, v66, v65
	v_max3_f32 v37, v37, 0, v38
	v_max_f32_e64 v71, |v40|, |v40|
	v_max_f32_e64 v72, |v60|, |v60|
	v_max_f32_e64 v73, |v41|, |v41|
	v_max_f32_e64 v74, |v61|, |v61|
	v_max_f32_e32 v63, v68, v67
	v_max_f32_e32 v64, v70, v69
	v_max3_f32 v37, v37, v39, v62
	v_max_f32_e32 v65, v72, v71
	v_max_f32_e32 v66, v74, v73
	v_max3_f32 v37, v37, v63, v64
	v_max3_f32 v37, v37, v65, v66
	ds_bpermute_b32 v38, v112, v37
	v_add_u32_e32 v39, s46, v52
	v_add_u32_e32 v52, s45, v53
	v_add_u32_e32 v53, s44, v54
	v_cndmask_b32_e64 v6, v6, v53, s[8:9]
	s_waitcnt lgkmcnt(0)
	v_max_f32_e32 v38, v38, v38
	v_max_f32_e32 v37, v37, v38
	ds_bpermute_b32 v38, v113, v37
	v_cndmask_b32_e64 v6, v6, v52, s[10:11]
	v_cndmask_b32_e64 v6, v6, v39, s[12:13]
	v_cndmask_b32_e64 v6, v6, v27, s[14:15]
	v_cndmask_b32_e64 v6, v6, v43, s[16:17]
	s_waitcnt lgkmcnt(0)
	v_max_f32_e32 v38, v38, v38
	v_max_f32_e32 v37, v37, v38
	ds_bpermute_b32 v38, v114, v37
	v_lshl_add_u32 v6, v6, 2, v11
	ds_write_b32 v6, v4
	ds_write_b32 v5, v1
	s_waitcnt vmcnt(1)
	v_mul_f32_e32 v1, v2, v45
	s_waitcnt lgkmcnt(2)
	v_max_f32_e32 v7, v38, v38
	v_max_f32_e32 v7, v37, v7
	ds_bpermute_b32 v37, v115, v7
	s_waitcnt vmcnt(0)
	v_mul_f32_e32 v2, v3, v47
	v_mul_f32_e32 v3, v12, v44
	ds_write_b32 v6, v1 offset:512
	ds_write_b32 v5, v2 offset:512
	ds_write_b32 v6, v3 offset:2048
	v_mul_f32_e32 v12, v12, v46
	s_waitcnt lgkmcnt(3)
	v_max_f32_e32 v4, v37, v37
	v_max_f32_e32 v4, v7, v4
	ds_bpermute_b32 v7, v116, v4
	ds_write_b32 v5, v12 offset:2048
	s_waitcnt lgkmcnt(1)
	v_max_f32_e32 v7, v7, v7
	v_max_f32_e32 v4, v4, v7
	ds_bpermute_b32 v7, v117, v4
	s_waitcnt lgkmcnt(0)
	v_max_f32_e32 v1, v7, v7
	v_max_f32_e32 v1, v4, v1
	v_div_scale_f32 v2, s[4:5], v1, v1, s33
	v_rcp_f32_e32 v3, v2
	v_div_scale_f32 v4, vcc, s33, v1, s33
	v_fma_f32 v5, -v2, v3, 1.0
	v_fmac_f32_e32 v3, v5, v3
	v_mul_f32_e32 v5, v4, v3
	v_fma_f32 v6, -v2, v5, v4
	v_fmac_f32_e32 v5, v6, v3
	v_fma_f32 v2, -v2, v5, v4
	v_div_fmas_f32 v2, v2, v3, v5
	v_div_fixup_f32 v2, v2, v1, s33
	v_cmp_lt_f32_e32 vcc, 0, v1
	s_nop 1
	v_cndmask_b32_e32 v12, 0, v2, vcc
	v_mul_f32_e32 v2, v12, v48
	v_mul_f32_e32 v3, v12, v34
	v_rndne_f32_e32 v2, v2
	v_rndne_f32_e32 v3, v3
	v_cvt_i32_f32_e32 v2, v2
	v_cvt_i32_f32_e32 v3, v3
	v_mul_f32_e32 v4, v12, v49
	v_mul_f32_e32 v5, v12, v35
	v_rndne_f32_e32 v4, v4
	v_add_u32_e32 v6, 8, v2
	v_and_b32_e32 v27, 15, v2
	v_add_u32_e32 v2, 8, v3
	v_lshlrev_b32_e32 v3, 4, v3
	v_cvt_i32_f32_e32 v4, v4
	v_and_b32_e32 v42, 0xf0, v3
	v_rndne_f32_e32 v3, v5
	v_cvt_i32_f32_e32 v3, v3
	v_lshl_add_u32 v7, v4, 4, v122
	v_lshlrev_b32_e32 v4, 8, v4
	v_lshrrev_b32_e32 v6, 4, v6
	v_and_b32_e32 v2, 0xf0, v2
	v_and_b32_e32 v43, 0xf00, v4
	v_lshl_add_u32 v4, v3, 8, v123
	v_and_or_b32 v2, v6, 15, v2
	v_and_b32_e32 v5, 0xf00, v7
	v_and_b32_e32 v4, 0xf000, v4
	v_mul_f32_e32 v6, v12, v50
	v_rndne_f32_e32 v6, v6
	v_or3_b32 v2, v2, v5, v4
	v_mul_f32_e32 v4, v12, v36
	v_cvt_i32_f32_e32 v6, v6
	v_rndne_f32_e32 v4, v4
	v_cvt_i32_f32_e32 v4, v4
	v_lshlrev_b32_e32 v3, 12, v3
	v_lshlrev_b32_e32 v5, 16, v6
	v_and_b32_e32 v44, 0xf000, v3
	v_lshl_add_u32 v3, v6, 12, v124
	v_and_b32_e32 v45, 0xf0000, v5
	v_lshl_add_u32 v5, v4, 16, v125
	v_and_b32_e32 v3, 0xf0000, v3
	v_and_b32_e32 v5, 0xf00000, v5
	v_or3_b32 v46, v2, v3, v5
	v_lshlrev_b32_e32 v2, 20, v4
	v_and_b32_e32 v47, 0xf00000, v2
	v_mul_f32_e32 v2, v12, v51
	v_rndne_f32_e32 v2, v2
	v_cvt_i32_f32_e32 v48, v2
	v_lshlrev_b64 v[2:3], 9, v[30:31]
	v_lshl_or_b32 v2, v10, 2, v2
	v_lshl_add_u64 v[6:7], s[20:21], 0, v[2:3]
	v_or_b32_e32 v4, 0x100, v2
	v_mov_b32_e32 v5, v3
	v_lshl_add_u64 v[34:35], s[20:21], 0, v[4:5]
	v_lshl_add_u64 v[36:37], s[24:25], 0, v[2:3]
	v_lshl_add_u64 v[38:39], s[24:25], 0, v[4:5]
	global_load_dword v2, v[6:7], off
	global_load_dword v3, v[34:35], off
	global_load_dword v4, v[36:37], off
	global_load_dword v5, v[38:39], off
	v_mul_f32_e32 v7, v12, v55
	v_rndne_f32_e32 v7, v7
	v_cvt_i32_f32_e32 v7, v7
	v_lshlrev_b32_e32 v34, 24, v48
	v_lshl_add_u32 v6, v48, 20, v126
	v_and_b32_e32 v35, 0xf000000, v34
	v_lshl_add_u32 v34, v7, 24, v127
	v_and_b32_e32 v6, 0xf000000, v6
	v_and_b32_e32 v34, 0xf0000000, v34
	v_or3_b32 v34, v46, v6, v34
	v_lshl_or_b32 v6, v7, 28, v27
	v_or3_b32 v6, v6, v42, v43
	v_or3_b32 v6, v6, v44, v45
	v_or3_b32 v35, v6, v47, v35
	v_mul_f32_e32 v6, v12, v56
	v_mul_f32_e32 v7, v12, v57
	v_rndne_f32_e32 v6, v6
	v_rndne_f32_e32 v7, v7
	v_cvt_i32_f32_e32 v6, v6
	v_cvt_i32_f32_e32 v7, v7
	v_mul_f32_e32 v37, v12, v58
	v_mul_f32_e32 v38, v12, v59
	v_rndne_f32_e32 v37, v37
	v_rndne_f32_e32 v38, v38
	v_cvt_i32_f32_e32 v37, v37
	v_cvt_i32_f32_e32 v38, v38
	v_add_u32_e32 v27, 8, v6
	v_add_u32_e32 v36, 8, v7
	v_lshrrev_b32_e32 v27, 4, v27
	v_and_b32_e32 v36, 0xf0, v36
	v_and_or_b32 v27, v27, 15, v36
	v_lshl_add_u32 v36, v37, 4, v122
	v_lshl_add_u32 v39, v38, 8, v123
	v_and_b32_e32 v36, 0xf00, v36
	v_and_b32_e32 v39, 0xf000, v39
	v_mul_f32_e32 v42, v12, v60
	v_or3_b32 v27, v27, v36, v39
	v_mul_f32_e32 v39, v12, v40
	v_rndne_f32_e32 v42, v42
	v_rndne_f32_e32 v39, v39
	v_cvt_i32_f32_e32 v42, v42
	v_cvt_i32_f32_e32 v39, v39
	v_mul_f32_e32 v43, v12, v61
	v_mul_f32_e32 v12, v12, v41
	v_rndne_f32_e32 v12, v12
	v_rndne_f32_e32 v43, v43
	v_cvt_i32_f32_e32 v12, v12
	v_lshlrev_b32_e32 v36, 12, v38
	v_cvt_i32_f32_e32 v43, v43
	v_and_b32_e32 v38, 0xf000, v36
	v_lshl_add_u32 v36, v42, 12, v124
	v_lshlrev_b32_e32 v40, 16, v42
	v_lshl_add_u32 v42, v39, 16, v125
	v_and_b32_e32 v6, 15, v6
	v_lshlrev_b32_e32 v7, 4, v7
	v_lshlrev_b32_e32 v37, 8, v37
	v_and_b32_e32 v36, 0xf0000, v36
	v_and_b32_e32 v42, 0xf00000, v42
	v_and_b32_e32 v7, 0xf0, v7
	v_and_b32_e32 v37, 0xf00, v37
	v_or3_b32 v27, v27, v36, v42
	v_lshlrev_b32_e32 v36, 20, v39
	v_lshl_or_b32 v6, v12, 28, v6
	v_and_b32_e32 v40, 0xf0000, v40
	v_and_b32_e32 v39, 0xf00000, v36
	v_lshl_add_u32 v36, v43, 20, v126
	v_lshlrev_b32_e32 v41, 24, v43
	v_lshl_add_u32 v42, v12, 24, v127
	v_or3_b32 v6, v6, v7, v37
	v_and_b32_e32 v36, 0xf000000, v36
	v_and_b32_e32 v41, 0xf000000, v41
	v_and_b32_e32 v42, 0xf0000000, v42
	v_or3_b32 v6, v6, v38, v40
	v_or3_b32 v36, v27, v36, v42
	v_or3_b32 v37, v6, v39, v41
	ds_write_b128 v128, v[34:37] offset:3584
	s_waitcnt vmcnt(3)
; __device__ __forceinline__ void p3_token(const Params& p, int tok, int lane, unsigned* rec, float& sh, int& hs8) {
;     ...
; #pragma unroll
;     for (int v = 0; v < 8; v++) {
;         const unsigned long long m0 = __ballot(k0 == v), m1 = __ballot(k1 == v);
;         const int c0 = __popcll(m0);
;         const int r0 = __builtin_amdgcn_mbcnt_hi((unsigned)(m0 >> 32), __builtin_amdgcn_mbcnt_lo((unsigned)m0, 0u));
;         const int r1 = __builtin_amdgcn_mbcnt_hi((unsigned)(m1 >> 32), __builtin_amdgcn_mbcnt_lo((unsigned)m1, 0u));
;         pos0 = (k0 == v) ? base + r0 : pos0;
;         pos1 = (k1 == v) ? base + c0 + r1 : pos1;
;         base += c0 + __popcll(m1);
;     }
;     const float* tsc = (const float*)(p.ws + OFF_UB + 33554432);
;     const f32x2 s0 = *(const f32x2*)(tsc + 2 * e0), s1 = *(const f32x2*)(tsc + 2 * e1);
	v_cmp_gt_u32_e32 vcc, s37, v2
	s_waitcnt vmcnt(2)
	v_cmp_gt_u32_e64 s[4:5], s37, v3
	s_bcnt1_i32_b64 s8, vcc
	s_and_saveexec_b64 s[6:7], s[4:5]
	v_mbcnt_lo_u32_b32 v0, s4, 0
	v_mbcnt_hi_u32_b32 v0, s5, v0
	v_add_u32_e32 v0, s8, v0
	s_or_b64 exec, exec, s[6:7]
	v_ashrrev_i32_e32 v6, 11, v2
	s_bcnt1_i32_b64 s42, s[4:5]
	v_cmp_eq_u32_e64 s[4:5], 1, v6
	v_ashrrev_i32_e32 v7, 11, v3
	s_add_i32 s42, s42, s8
	s_bcnt1_i32_b64 s8, s[4:5]
	v_cmp_eq_u32_e64 s[6:7], 1, v7
	s_add_i32 s43, s42, s8
	s_and_saveexec_b64 s[8:9], s[6:7]
	v_mbcnt_lo_u32_b32 v0, s6, 0
	v_mbcnt_hi_u32_b32 v0, s7, v0
	v_add_u32_e32 v0, s43, v0
	s_or_b64 exec, exec, s[8:9]
	s_bcnt1_i32_b64 s6, s[6:7]
	s_add_i32 s43, s43, s6
	v_cmp_eq_u32_e64 s[6:7], 2, v6
	s_bcnt1_i32_b64 s10, s[6:7]
	v_cmp_eq_u32_e64 s[8:9], 2, v7
	s_add_i32 s44, s43, s10
	s_and_saveexec_b64 s[10:11], s[8:9]
	v_mbcnt_lo_u32_b32 v0, s8, 0
	v_mbcnt_hi_u32_b32 v0, s9, v0
	v_add_u32_e32 v0, s44, v0
	s_or_b64 exec, exec, s[10:11]
	s_bcnt1_i32_b64 s8, s[8:9]
	s_add_i32 s44, s44, s8
	v_cmp_eq_u32_e64 s[8:9], 3, v6
	s_bcnt1_i32_b64 s12, s[8:9]
	v_cmp_eq_u32_e64 s[10:11], 3, v7
	s_add_i32 s45, s44, s12
	s_and_saveexec_b64 s[12:13], s[10:11]
	v_mbcnt_lo_u32_b32 v0, s10, 0
	v_mbcnt_hi_u32_b32 v0, s11, v0
	v_add_u32_e32 v0, s45, v0
	s_or_b64 exec, exec, s[12:13]
	s_bcnt1_i32_b64 s10, s[10:11]
	s_add_i32 s45, s45, s10
	v_cmp_eq_u32_e64 s[10:11], 4, v6
	s_bcnt1_i32_b64 s14, s[10:11]
	v_cmp_eq_u32_e64 s[12:13], 4, v7
	s_add_i32 s46, s45, s14
	s_and_saveexec_b64 s[14:15], s[12:13]
	v_mbcnt_lo_u32_b32 v0, s12, 0
	v_mbcnt_hi_u32_b32 v0, s13, v0
	v_add_u32_e32 v0, s46, v0
	s_or_b64 exec, exec, s[14:15]
	s_bcnt1_i32_b64 s12, s[12:13]
	s_add_i32 s46, s46, s12
	v_cmp_eq_u32_e64 s[12:13], 5, v6
	s_bcnt1_i32_b64 s16, s[12:13]
	v_cmp_eq_u32_e64 s[14:15], 5, v7
	s_add_i32 s47, s46, s16
	s_and_saveexec_b64 s[16:17], s[14:15]
	v_mbcnt_lo_u32_b32 v0, s14, 0
	v_mbcnt_hi_u32_b32 v0, s15, v0
	v_add_u32_e32 v0, s47, v0
	s_or_b64 exec, exec, s[16:17]
	s_bcnt1_i32_b64 s14, s[14:15]
	s_add_i32 s47, s47, s14
	v_cmp_eq_u32_e64 s[14:15], 6, v6
	s_bcnt1_i32_b64 s18, s[14:15]
	v_cmp_eq_u32_e64 s[16:17], 6, v7
	s_add_i32 s48, s47, s18
	s_and_saveexec_b64 s[18:19], s[16:17]
	v_mbcnt_lo_u32_b32 v0, s16, 0
	v_mbcnt_hi_u32_b32 v0, s17, v0
	v_add_u32_e32 v0, s48, v0
	s_or_b64 exec, exec, s[18:19]
	s_bcnt1_i32_b64 s16, s[16:17]
	s_add_i32 s48, s48, s16
	v_cmp_eq_u32_e64 s[16:17], 7, v6
	v_cmp_eq_u32_e64 s[18:19], 7, v7
	s_and_saveexec_b64 s[34:35], s[18:19]
	s_bcnt1_i32_b64 s49, s[16:17]
	v_mbcnt_lo_u32_b32 v0, s18, 0
	s_add_i32 s49, s48, s49
	v_mbcnt_hi_u32_b32 v0, s19, v0
	v_add_u32_e32 v0, s49, v0
	s_or_b64 exec, exec, s[34:35]
	v_lshlrev_b32_e32 v6, 1, v2
	v_ashrrev_i32_e32 v7, 31, v6
	v_lshlrev_b32_e32 v34, 1, v3
	v_lshl_add_u64 v[6:7], v[6:7], 2, s[26:27]
	v_ashrrev_i32_e32 v35, 31, v34
	v_lshl_add_u64 v[34:35], v[34:35], 2, s[26:27]
	global_load_dwordx2 v[36:37], v[6:7], off
	global_load_dwordx2 v[38:39], v[34:35], off
	v_mbcnt_lo_u32_b32 v41, s4, 0
	v_mbcnt_lo_u32_b32 v42, vcc_lo, 0
	v_mbcnt_lo_u32_b32 v40, s6, 0
	v_mbcnt_hi_u32_b32 v41, s5, v41
	v_mbcnt_hi_u32_b32 v42, vcc_hi, v42
	v_mbcnt_lo_u32_b32 v34, s8, 0
	v_mbcnt_hi_u32_b32 v40, s7, v40
	v_add_u32_e32 v41, s42, v41
	v_cndmask_b32_e32 v42, 0, v42, vcc
	v_mbcnt_lo_u32_b32 v27, s10, 0
	v_mbcnt_hi_u32_b32 v34, s9, v34
	v_add_u32_e32 v40, s43, v40
	v_cndmask_b32_e64 v41, v42, v41, s[4:5]
	v_mbcnt_lo_u32_b32 v12, s12, 0
	v_mbcnt_hi_u32_b32 v27, s11, v27
	v_add_u32_e32 v34, s44, v34
	v_cndmask_b32_e64 v40, v41, v40, s[6:7]
	v_mbcnt_lo_u32_b32 v7, s14, 0
	v_mbcnt_hi_u32_b32 v12, s13, v12
	v_add_u32_e32 v27, s45, v27
	v_cndmask_b32_e64 v34, v40, v34, s[8:9]
	v_mbcnt_lo_u32_b32 v6, s16, 0
	v_mbcnt_hi_u32_b32 v7, s15, v7
	v_add_u32_e32 v12, s46, v12
	v_cndmask_b32_e64 v27, v34, v27, s[10:11]
	v_mbcnt_hi_u32_b32 v6, s17, v6
	v_add_u32_e32 v7, s47, v7
	v_cndmask_b32_e64 v12, v27, v12, s[12:13]
	v_add_u32_e32 v6, s48, v6
	v_cndmask_b32_e64 v7, v12, v7, s[14:15]
	v_cndmask_b32_e64 v6, v7, v6, s[16:17]
	v_mul_f32_e32 v1, 0x3c09ae41, v1
	v_lshl_add_u32 v6, v6, 2, v11
	v_lshl_add_u32 v0, v0, 2, v11
	ds_write_b32 v6, v2 offset:2560
	ds_write_b32 v0, v3 offset:2560
	v_mov_b32_e32 v35, v13
	v_mov_b32_e32 v41, v13
	s_mov_b32 s5, 0
	s_waitcnt vmcnt(1)
; __device__ __forceinline__ void p3_load_u(u32x2 (&ur)[4], P3Sc& sc, const unsigned char* __restrict__ UQ, const float* __restrict__ tsc,
;                                           int lane, int ul, int g, const unsigned* rec) {
; #pragma unroll
;     for (int u = 0; u < 4; u++) ur[u] = *(const u32x2*)(UQ + (size_t)rec[4 * g + u] * 512 + lane * 8);
;     sc.gm = __uint_as_float(rec[128 + 4 * g + ul]);
;     sc.su = __uint_as_float(rec[512 + 4 * g + ul]);
;     sc.sv = 1.f;
; }
; __device__ __forceinline__ void p3_load_v(u32x2 (&vr)[4], const unsigned char* __restrict__ VQ, int lane, int g, const unsigned* rec) {
; #pragma unroll
;     for (int u = 0; u < 4; u++) vr[u] = *(const u32x2*)(VQ + (size_t)rec[4 * g + u] * 512 + lane * 8);
; }
; __device__ __forceinline__ void p3_token(const Params& p, int tok, int lane, unsigned* rec, float& sh, int& hs8) {
;     ...
;     const f32x2 s0 = *(const f32x2*)(tsc + 2 * e0), s1 = *(const f32x2*)(tsc + 2 * e1);
;     rec[pos0] = (unsigned)e0; rec[pos1] = (unsigned)e1;
;     rec[128 + pos0] = __float_as_uint(g0 * s0[1]); rec[128 + pos1] = __float_as_uint(g1 * s1[1]);
;     rec[512 + pos0] = __float_as_uint(sh * s0[0]); rec[512 + pos1] = __float_as_uint(sh * s1[0]);
	v_mul_f32_e32 v2, v4, v37
	s_waitcnt vmcnt(0)
	v_mul_f32_e32 v3, v5, v39
	v_mul_f32_e32 v4, v1, v36
	v_mul_f32_e32 v1, v1, v38
	ds_write_b32 v6, v2 offset:3072
	ds_write_b32 v0, v3 offset:3072
	ds_write_b32 v6, v4 offset:4608
	ds_write_b32 v0, v1 offset:4608
	ds_read_b128 v[0:3], v11
	ds_read_b128 v[4:7], v11 offset:2560
	v_mov_b32_e32 v37, v13
	v_mov_b32_e32 v39, v13
	s_waitcnt lgkmcnt(1)
	v_mov_b32_e32 v12, v0
	v_mov_b32_e32 v34, v1
	v_mov_b32_e32 v36, v3
	s_waitcnt lgkmcnt(0)
	v_mov_b32_e32 v38, v5
	v_mov_b32_e32 v40, v7
	v_lshlrev_b64 v[0:1], 9, v[34:35]
	v_lshlrev_b64 v[34:35], 9, v[12:13]
	v_mov_b32_e32 v12, v2
	v_lshlrev_b64 v[2:3], 9, v[36:37]
	v_lshlrev_b64 v[36:37], 9, v[38:39]
	v_lshlrev_b64 v[38:39], 9, v[40:41]
	v_lshl_add_u64 v[40:41], v[14:15], 0, v[34:35]
	v_lshlrev_b64 v[44:45], 9, v[12:13]
	v_lshl_add_u64 v[42:43], v[14:15], 0, v[0:1]
	v_lshl_add_u64 v[46:47], v[14:15], 0, v[2:3]
	v_lshl_add_u64 v[34:35], v[16:17], 0, v[34:35]
	v_lshl_add_u64 v[0:1], v[16:17], 0, v[0:1]
	v_lshl_add_u64 v[2:3], v[16:17], 0, v[2:3]
	v_mov_b32_e32 v12, v4
	v_lshl_add_u64 v[50:51], v[14:15], 0, v[44:45]
	v_lshl_add_u64 v[44:45], v[16:17], 0, v[44:45]
	global_load_dwordx2 v[80:81], v[40:41], off
	global_load_dwordx2 v[74:75], v[42:43], off
	global_load_dwordx2 v[84:85], v[50:51], off
	global_load_dwordx2 v[82:83], v[46:47], off
	global_load_dwordx2 v[72:73], v[34:35], off
	global_load_dwordx2 v[70:71], v[0:1], off
	global_load_dwordx2 v[62:63], v[44:45], off
	global_load_dwordx2 v[58:59], v[2:3], off
	v_lshlrev_b64 v[52:53], 9, v[12:13]
	v_mov_b32_e32 v12, v6
	v_lshl_add_u64 v[0:1], v[14:15], 0, v[52:53]
	v_lshlrev_b64 v[2:3], 9, v[12:13]
	v_lshl_add_u64 v[4:5], v[14:15], 0, v[36:37]
	v_lshl_add_u64 v[48:49], v[14:15], 0, v[38:39]
	v_lshl_add_u64 v[6:7], v[14:15], 0, v[2:3]
	global_load_dwordx2 v[66:67], v[0:1], off
	global_load_dwordx2 v[60:61], v[4:5], off
	global_load_dwordx2 v[68:69], v[6:7], off
	global_load_dwordx2 v[64:65], v[48:49], off
	v_lshl_add_u64 v[0:1], v[16:17], 0, v[52:53]
	v_lshl_add_u64 v[4:5], v[16:17], 0, v[36:37]
	v_lshl_add_u64 v[2:3], v[16:17], 0, v[2:3]
	v_lshl_add_u64 v[6:7], v[16:17], 0, v[38:39]
	global_load_dwordx2 v[40:41], v[0:1], off
	global_load_dwordx2 v[38:39], v[4:5], off
	global_load_dwordx2 v[36:37], v[2:3], off
	global_load_dwordx2 v[34:35], v[6:7], off
	ds_read2st64_b32 v[76:77], v119 offset0:2 offset1:8
	ds_read2st64_b32 v[78:79], v119 offset0:12 offset1:18
	ds_read_b128 v[4:7], v128 offset:1024
	ds_read_b128 v[0:3], v128 offset:3584
	v_mov_b32_e32 v42, 0
	v_mov_b32_e32 v43, v42
	v_mov_b32_e32 v44, v42
	v_mov_b32_e32 v45, v42
	v_mov_b32_e32 v46, v42
	v_mov_b32_e32 v47, v42
	v_mov_b32_e32 v48, v42
	v_mov_b32_e32 v49, v42
	v_mov_b32_e32 v50, v42
	v_mov_b32_e32 v51, v42
	v_mov_b32_e32 v52, v42
	v_mov_b32_e32 v53, v42
	v_mov_b32_e32 v86, v42
	v_mov_b32_e32 v87, v42
	v_mov_b32_e32 v88, v42
	v_mov_b32_e32 v89, v42
	v_mov_b32_e32 v90, v42
	v_mov_b32_e32 v91, v42
	v_mov_b32_e32 v92, v42
	v_mov_b32_e32 v93, v42
	v_mov_b32_e32 v94, v42
	v_mov_b32_e32 v95, v42
	v_mov_b32_e32 v96, v42
	v_mov_b32_e32 v97, v42
	v_mov_b32_e32 v98, v42
	v_mov_b32_e32 v99, v42
	v_mov_b32_e32 v100, v42
	v_mov_b32_e32 v101, v42
	v_mov_b32_e32 v54, v42
	v_mov_b32_e32 v55, v42
	v_mov_b32_e32 v56, v42
	v_mov_b32_e32 v57, v42
	s_waitcnt lgkmcnt(0)
	v_cndmask_b32_e64 v76, v76, v78, s[54:55]
	v_cndmask_b32_e64 v77, v77, v79, s[54:55]
	.p2alignl 6, 3212836864
